# sample_out_block epilogue: the 16 residual elements requested together instead of 16 serial load-wait-store round trips
# speedup vs baseline: 1.0409x; 1.0015x over previous
; #define MFMA16(a, b, c) __builtin_amdgcn_mfma_f32_16x16x32_bf16((a), (b), (c), 0, 0, 0)
; __device__ __forceinline__ void sample_out_block(LAS unsigned char* lds, const bf16_t* A, const bf16_t* Bt, int K, bf16_t* xb, float* sspart, int blk, int tid) {
;     ...
;     {
;         const bf16_t* ap = A + (size_t)(r0 + l15) * K + wave * kq + 8 * g;
;         const bf16_t* bp = Bt + (size_t)(64 * cg + l15) * K + wave * kq + 8 * g;
;         bf16x8 af[2][2], bf[2][4], afn[2][2], bfn[2][4];
; #pragma unroll
;         for (int s = 0; s < 2; ++s) {
; #pragma unroll
;             for (int ra = 0; ra < 2; ++ra) af[s][ra] = *(const bf16x8*)(ap + (size_t)(16 * ra) * K + 32 * s);
; #pragma unroll
;             for (int nt = 0; nt < 4; ++nt) bf[s][nt] = *(const bf16x8*)(bp + (size_t)(16 * nt) * K + 32 * s);
;         }
;         for (int k0 = 0; k0 < kq; k0 += 64) {
;             const int k1 = (k0 + 64 < kq) ? k0 + 64 : k0;
; #pragma unroll
;             for (int s = 0; s < 2; ++s) {
; #pragma unroll
;                 for (int ra = 0; ra < 2; ++ra) afn[s][ra] = *(const bf16x8*)(ap + (size_t)(16 * ra) * K + k1 + 32 * s);
; #pragma unroll
;                 for (int nt = 0; nt < 4; ++nt) bfn[s][nt] = *(const bf16x8*)(bp + (size_t)(16 * nt) * K + k1 + 32 * s);
;             }
; #pragma unroll
;             for (int s = 0; s < 2; ++s)
; #pragma unroll
;                 for (int ra = 0; ra < 2; ++ra)
; #pragma unroll
;                     for (int nt = 0; nt < 4; ++nt) acc[ra][nt] = MFMA16(af[s][ra], bf[s][nt], acc[ra][nt]);
.LBB0_542:
	s_and_b32 s27, s34, 0xffffffe0
	s_addk_i32 s27, 0x2000
	s_and_b32 s26, s34, 31
	v_or_b32_e32 v8, s27, v30
	v_ashrrev_i32_e32 v9, 31, v8
	s_lshl_b32 s35, s26, 6
	v_lshlrev_b64 v[8:9], 13, v[8:9]
	v_or_b32_e32 v0, s35, v30
	v_lshl_add_u64 v[10:11], v[2:3], 0, v[8:9]
	v_lshlrev_b32_e32 v0, 13, v0
	v_lshl_add_u64 v[16:17], v[4:5], 0, v[0:1]
	v_add_co_u32_e32 v8, vcc, 0x20000, v10
	s_mov_b64 s[10:11], vcc
	v_add_co_u32_e32 v12, vcc, 0x20000, v16
	v_readfirstlane_b32 s36, v139
	s_lshr_b32 s36, s36, 6
	s_and_b32 s37, s34, 0xffffffe0
	s_addk_i32 s37, 0x2000
	s_and_b32 s38, s34, 31
	s_lshl_b32 s38, s38, 6
	s_lshl_b32 s39, s37, 13
	s_mul_i32 s40, s36, 0x400
	s_add_u32 s42, s24, s39
	s_addc_u32 s43, s25, 0
	s_add_u32 s42, s42, s40
	s_addc_u32 s43, s43, 0
	s_lshl_b32 s41, s30, 1
	s_lshl_b32 s39, s38, 13
	s_add_u32 s44, s28, s41
	s_addc_u32 s45, s29, 0
	s_add_u32 s44, s44, s39
	s_addc_u32 s45, s45, 0
	s_add_u32 s44, s44, s40
	s_addc_u32 s45, s45, 0
	v_lshrrev_b32_e32 v227, 3, v215
	v_and_b32_e32 v228, 7, v215
	v_lshlrev_b32_e32 v198, 13, v227
	v_lshl_add_u32 v198, v228, 4, v198
	v_add_u32_e32 v199, 0x10000, v198
	v_add_u32_e32 v200, 0x20000, v198
	v_add_u32_e32 v201, 0x30000, v198
	v_add_u32_e32 v202, 0x40000, v198
	v_add_u32_e32 v203, 0x50000, v198
	v_add_u32_e32 v204, 0x60000, v198
	v_add_u32_e32 v205, 0x70000, v198
	s_lshl_b32 s46, s36, 13
	s_mul_i32 s47, s36, 0x1800
	s_add_i32 s47, s47, 0x10000
	v_mul_u32_u24_e32 v206, 0x90, v227
	v_lshl_add_u32 v206, v228, 4, v206
	v_add_u32_e32 v207, s47, v206
	v_add_u32_e32 v206, s46, v206
	v_and_b32_e32 v227, 15, v215
	v_lshrrev_b32_e32 v228, 4, v215
	v_mul_u32_u24_e32 v208, 0x90, v227
	v_lshl_add_u32 v208, v228, 4, v208
	v_add_u32_e32 v209, s47, v208
	v_add_u32_e32 v208, s46, v208
	v_add_u32_e32 v226, 0x1b00, v208
	v_subrev_u32_e32 v228, 0x480, v209
	v_cmp_gt_u32_e32 vcc, 8, v227
	v_cndmask_b32_e32 v226, v228, v226, vcc
	global_load_dwordx4 v[34:37], v198, s[42:43]
	global_load_dwordx4 v[38:41], v199, s[42:43]
	global_load_dwordx4 v[42:45], v200, s[42:43]
	global_load_dwordx4 v[46:49], v201, s[42:43]
	global_load_dwordx4 v[50:53], v198, s[44:45]
	global_load_dwordx4 v[54:57], v199, s[44:45]
	global_load_dwordx4 v[58:61], v200, s[44:45]
	global_load_dwordx4 v[62:65], v201, s[44:45]
	global_load_dwordx4 v[66:69], v202, s[44:45]
	global_load_dwordx4 v[70:73], v203, s[44:45]
	global_load_dwordx4 v[74:77], v204, s[44:45]
	global_load_dwordx4 v[78:81], v205, s[44:45]
	global_load_dwordx4 v[82:85], v198, s[42:43] offset:128
	global_load_dwordx4 v[86:89], v199, s[42:43] offset:128
	global_load_dwordx4 v[90:93], v200, s[42:43] offset:128
	global_load_dwordx4 v[94:97], v201, s[42:43] offset:128
	global_load_dwordx4 v[98:101], v198, s[44:45] offset:128
	global_load_dwordx4 v[102:105], v199, s[44:45] offset:128
	global_load_dwordx4 v[106:109], v200, s[44:45] offset:128
	global_load_dwordx4 v[110:113], v201, s[44:45] offset:128
	global_load_dwordx4 v[114:117], v202, s[44:45] offset:128
	global_load_dwordx4 v[118:121], v203, s[44:45] offset:128
	global_load_dwordx4 v[122:125], v204, s[44:45] offset:128
	global_load_dwordx4 v[126:129], v205, s[44:45] offset:128
	s_waitcnt vmcnt(12)
	ds_write_b128 v206, v[34:37]
	ds_write_b128 v206, v[38:41] offset:1152
	ds_write_b128 v206, v[42:45] offset:2304
	ds_write_b128 v206, v[46:49] offset:3456
	ds_write_b128 v206, v[50:53] offset:4608
	ds_write_b128 v206, v[54:57] offset:5760
	ds_write_b128 v206, v[58:61] offset:6912
	ds_write_b128 v207, v[62:65]
	ds_write_b128 v207, v[66:69] offset:1152
	ds_write_b128 v207, v[70:73] offset:2304
	ds_write_b128 v207, v[74:77] offset:3456
	ds_write_b128 v207, v[78:81] offset:4608
	global_load_dwordx4 v[34:37], v198, s[42:43] offset:256
	global_load_dwordx4 v[38:41], v199, s[42:43] offset:256
	global_load_dwordx4 v[42:45], v200, s[42:43] offset:256
	global_load_dwordx4 v[46:49], v201, s[42:43] offset:256
	global_load_dwordx4 v[50:53], v198, s[44:45] offset:256
	global_load_dwordx4 v[54:57], v199, s[44:45] offset:256
	global_load_dwordx4 v[58:61], v200, s[44:45] offset:256
	global_load_dwordx4 v[62:65], v201, s[44:45] offset:256
	global_load_dwordx4 v[66:69], v202, s[44:45] offset:256
	global_load_dwordx4 v[70:73], v203, s[44:45] offset:256
	global_load_dwordx4 v[74:77], v204, s[44:45] offset:256
	global_load_dwordx4 v[78:81], v205, s[44:45] offset:256
	ds_read_b128 v[146:149], v208 offset:0
	ds_read_b128 v[150:153], v208 offset:2304
	ds_read_b128 v[154:157], v208 offset:4608
	ds_read_b128 v[158:161], v226
	ds_read_b128 v[162:165], v209 offset:1152
	ds_read_b128 v[166:169], v209 offset:3456
	ds_read_b128 v[170:173], v208 offset:64
	ds_read_b128 v[174:177], v208 offset:2368
	ds_read_b128 v[178:181], v208 offset:4672
	ds_read_b128 v[182:185], v226 offset:64
	ds_read_b128 v[186:189], v209 offset:1216
	ds_read_b128 v[190:193], v209 offset:3520
	s_waitcnt lgkmcnt(6)
	v_mfma_f32_16x16x32_bf16 v[8:11], v[146:149], v[154:157], 0
	v_mfma_f32_16x16x32_bf16 v[12:15], v[146:149], v[158:161], 0
	v_mfma_f32_16x16x32_bf16 v[16:19], v[146:149], v[162:165], 0
	v_mfma_f32_16x16x32_bf16 v[20:23], v[146:149], v[166:169], 0
	v_mfma_f32_16x16x32_bf16 v[24:27], v[150:153], v[154:157], 0
	v_mfma_f32_16x16x32_bf16 v[130:133], v[150:153], v[158:161], 0
	v_mfma_f32_16x16x32_bf16 v[134:137], v[150:153], v[162:165], 0
	v_mfma_f32_16x16x32_bf16 v[194:197], v[150:153], v[166:169], 0
	s_waitcnt lgkmcnt(0)
; #define MFMA16(a, b, c) __builtin_amdgcn_mfma_f32_16x16x32_bf16((a), (b), (c), 0, 0, 0)
; __device__ __forceinline__ void sample_out_block(LAS unsigned char* lds, const bf16_t* A, const bf16_t* Bt, int K, bf16_t* xb, float* sspart, int blk, int tid) {
;     ...
;         for (int k0 = 0; k0 < kq; k0 += 64) {
;             const int k1 = (k0 + 64 < kq) ? k0 + 64 : k0;
; #pragma unroll
;             for (int s = 0; s < 2; ++s) {
; #pragma unroll
;                 for (int ra = 0; ra < 2; ++ra) afn[s][ra] = *(const bf16x8*)(ap + (size_t)(16 * ra) * K + k1 + 32 * s);
; #pragma unroll
;                 for (int nt = 0; nt < 4; ++nt) bfn[s][nt] = *(const bf16x8*)(bp + (size_t)(16 * nt) * K + k1 + 32 * s);
;             }
; #pragma unroll
;             for (int s = 0; s < 2; ++s)
; #pragma unroll
;                 for (int ra = 0; ra < 2; ++ra)
; #pragma unroll
;                     for (int nt = 0; nt < 4; ++nt) acc[ra][nt] = MFMA16(af[s][ra], bf[s][nt], acc[ra][nt]);
	v_mfma_f32_16x16x32_bf16 v[8:11], v[170:173], v[178:181], v[8:11]
	v_mfma_f32_16x16x32_bf16 v[12:15], v[170:173], v[182:185], v[12:15]
	v_mfma_f32_16x16x32_bf16 v[16:19], v[170:173], v[186:189], v[16:19]
	v_mfma_f32_16x16x32_bf16 v[20:23], v[170:173], v[190:193], v[20:23]
	v_mfma_f32_16x16x32_bf16 v[24:27], v[174:177], v[178:181], v[24:27]
	v_mfma_f32_16x16x32_bf16 v[130:133], v[174:177], v[182:185], v[130:133]
	v_mfma_f32_16x16x32_bf16 v[134:137], v[174:177], v[186:189], v[134:137]
	v_mfma_f32_16x16x32_bf16 v[194:197], v[174:177], v[190:193], v[194:197]
	s_waitcnt vmcnt(12)
	ds_write_b128 v206, v[82:85]
	ds_write_b128 v206, v[86:89] offset:1152
	ds_write_b128 v206, v[90:93] offset:2304
	ds_write_b128 v206, v[94:97] offset:3456
	ds_write_b128 v206, v[98:101] offset:4608
	ds_write_b128 v206, v[102:105] offset:5760
	ds_write_b128 v206, v[106:109] offset:6912
	ds_write_b128 v207, v[110:113]
	ds_write_b128 v207, v[114:117] offset:1152
	ds_write_b128 v207, v[118:121] offset:2304
	ds_write_b128 v207, v[122:125] offset:3456
	ds_write_b128 v207, v[126:129] offset:4608
	global_load_dwordx4 v[82:85], v198, s[42:43] offset:384
	global_load_dwordx4 v[86:89], v199, s[42:43] offset:384
	global_load_dwordx4 v[90:93], v200, s[42:43] offset:384
	global_load_dwordx4 v[94:97], v201, s[42:43] offset:384
	global_load_dwordx4 v[98:101], v198, s[44:45] offset:384
	global_load_dwordx4 v[102:105], v199, s[44:45] offset:384
	global_load_dwordx4 v[106:109], v200, s[44:45] offset:384
	global_load_dwordx4 v[110:113], v201, s[44:45] offset:384
	global_load_dwordx4 v[114:117], v202, s[44:45] offset:384
	global_load_dwordx4 v[118:121], v203, s[44:45] offset:384
	global_load_dwordx4 v[122:125], v204, s[44:45] offset:384
	global_load_dwordx4 v[126:129], v205, s[44:45] offset:384
	ds_read_b128 v[146:149], v208 offset:0
	ds_read_b128 v[150:153], v208 offset:2304
	ds_read_b128 v[154:157], v208 offset:4608
	ds_read_b128 v[158:161], v226
	ds_read_b128 v[162:165], v209 offset:1152
	ds_read_b128 v[166:169], v209 offset:3456
	ds_read_b128 v[170:173], v208 offset:64
	ds_read_b128 v[174:177], v208 offset:2368
	ds_read_b128 v[178:181], v208 offset:4672
	ds_read_b128 v[182:185], v226 offset:64
	ds_read_b128 v[186:189], v209 offset:1216
	ds_read_b128 v[190:193], v209 offset:3520
	s_waitcnt lgkmcnt(6)
	v_mfma_f32_16x16x32_bf16 v[8:11], v[146:149], v[154:157], v[8:11]
	v_mfma_f32_16x16x32_bf16 v[12:15], v[146:149], v[158:161], v[12:15]
	v_mfma_f32_16x16x32_bf16 v[16:19], v[146:149], v[162:165], v[16:19]
	v_mfma_f32_16x16x32_bf16 v[20:23], v[146:149], v[166:169], v[20:23]
	v_mfma_f32_16x16x32_bf16 v[24:27], v[150:153], v[154:157], v[24:27]
	v_mfma_f32_16x16x32_bf16 v[130:133], v[150:153], v[158:161], v[130:133]
	v_mfma_f32_16x16x32_bf16 v[134:137], v[150:153], v[162:165], v[134:137]
	v_mfma_f32_16x16x32_bf16 v[194:197], v[150:153], v[166:169], v[194:197]
	s_waitcnt lgkmcnt(0)
	v_mfma_f32_16x16x32_bf16 v[8:11], v[170:173], v[178:181], v[8:11]
	v_mfma_f32_16x16x32_bf16 v[12:15], v[170:173], v[182:185], v[12:15]
	v_mfma_f32_16x16x32_bf16 v[16:19], v[170:173], v[186:189], v[16:19]
	v_mfma_f32_16x16x32_bf16 v[20:23], v[170:173], v[190:193], v[20:23]
	v_mfma_f32_16x16x32_bf16 v[24:27], v[174:177], v[178:181], v[24:27]
	v_mfma_f32_16x16x32_bf16 v[130:133], v[174:177], v[182:185], v[130:133]
	v_mfma_f32_16x16x32_bf16 v[134:137], v[174:177], v[186:189], v[134:137]
	v_mfma_f32_16x16x32_bf16 v[194:197], v[174:177], v[190:193], v[194:197]
	s_waitcnt vmcnt(12)
	ds_write_b128 v206, v[34:37]
	ds_write_b128 v206, v[38:41] offset:1152
	ds_write_b128 v206, v[42:45] offset:2304
	ds_write_b128 v206, v[46:49] offset:3456
	ds_write_b128 v206, v[50:53] offset:4608
	ds_write_b128 v206, v[54:57] offset:5760
	ds_write_b128 v206, v[58:61] offset:6912
	ds_write_b128 v207, v[62:65]
	ds_write_b128 v207, v[66:69] offset:1152
	ds_write_b128 v207, v[70:73] offset:2304
	ds_write_b128 v207, v[74:77] offset:3456
	ds_write_b128 v207, v[78:81] offset:4608
	global_load_dwordx4 v[34:37], v198, s[42:43] offset:512
	global_load_dwordx4 v[38:41], v199, s[42:43] offset:512
	global_load_dwordx4 v[42:45], v200, s[42:43] offset:512
	global_load_dwordx4 v[46:49], v201, s[42:43] offset:512
	global_load_dwordx4 v[50:53], v198, s[44:45] offset:512
	global_load_dwordx4 v[54:57], v199, s[44:45] offset:512
	global_load_dwordx4 v[58:61], v200, s[44:45] offset:512
	global_load_dwordx4 v[62:65], v201, s[44:45] offset:512
	global_load_dwordx4 v[66:69], v202, s[44:45] offset:512
	global_load_dwordx4 v[70:73], v203, s[44:45] offset:512
	global_load_dwordx4 v[74:77], v204, s[44:45] offset:512
	global_load_dwordx4 v[78:81], v205, s[44:45] offset:512
	ds_read_b128 v[146:149], v208 offset:0
	ds_read_b128 v[150:153], v208 offset:2304
	ds_read_b128 v[154:157], v208 offset:4608
	ds_read_b128 v[158:161], v226
	ds_read_b128 v[162:165], v209 offset:1152
	ds_read_b128 v[166:169], v209 offset:3456
	ds_read_b128 v[170:173], v208 offset:64
	ds_read_b128 v[174:177], v208 offset:2368
	ds_read_b128 v[178:181], v208 offset:4672
	ds_read_b128 v[182:185], v226 offset:64
	ds_read_b128 v[186:189], v209 offset:1216
	ds_read_b128 v[190:193], v209 offset:3520
	s_waitcnt lgkmcnt(6)
	v_mfma_f32_16x16x32_bf16 v[8:11], v[146:149], v[154:157], v[8:11]
	v_mfma_f32_16x16x32_bf16 v[12:15], v[146:149], v[158:161], v[12:15]
	v_mfma_f32_16x16x32_bf16 v[16:19], v[146:149], v[162:165], v[16:19]
	v_mfma_f32_16x16x32_bf16 v[20:23], v[146:149], v[166:169], v[20:23]
	v_mfma_f32_16x16x32_bf16 v[24:27], v[150:153], v[154:157], v[24:27]
	v_mfma_f32_16x16x32_bf16 v[130:133], v[150:153], v[158:161], v[130:133]
	v_mfma_f32_16x16x32_bf16 v[134:137], v[150:153], v[162:165], v[134:137]
	v_mfma_f32_16x16x32_bf16 v[194:197], v[150:153], v[166:169], v[194:197]
	s_waitcnt lgkmcnt(0)
; #define MFMA16(a, b, c) __builtin_amdgcn_mfma_f32_16x16x32_bf16((a), (b), (c), 0, 0, 0)
; __device__ __forceinline__ void sample_out_block(LAS unsigned char* lds, const bf16_t* A, const bf16_t* Bt, int K, bf16_t* xb, float* sspart, int blk, int tid) {
;     ...
;         for (int k0 = 0; k0 < kq; k0 += 64) {
;             const int k1 = (k0 + 64 < kq) ? k0 + 64 : k0;
; #pragma unroll
;             for (int s = 0; s < 2; ++s) {
; #pragma unroll
;                 for (int ra = 0; ra < 2; ++ra) afn[s][ra] = *(const bf16x8*)(ap + (size_t)(16 * ra) * K + k1 + 32 * s);
; #pragma unroll
;                 for (int nt = 0; nt < 4; ++nt) bfn[s][nt] = *(const bf16x8*)(bp + (size_t)(16 * nt) * K + k1 + 32 * s);
;             }
; #pragma unroll
;             for (int s = 0; s < 2; ++s)
; #pragma unroll
;                 for (int ra = 0; ra < 2; ++ra)
; #pragma unroll
;                     for (int nt = 0; nt < 4; ++nt) acc[ra][nt] = MFMA16(af[s][ra], bf[s][nt], acc[ra][nt]);
; #pragma unroll
;             for (int s = 0; s < 2; ++s) {
; #pragma unroll
;                 for (int ra = 0; ra < 2; ++ra) af[s][ra] = afn[s][ra];
; #pragma unroll
;                 for (int nt = 0; nt < 4; ++nt) bf[s][nt] = bfn[s][nt];
;             }
;         }
	v_mfma_f32_16x16x32_bf16 v[8:11], v[170:173], v[178:181], v[8:11]
	v_mfma_f32_16x16x32_bf16 v[12:15], v[170:173], v[182:185], v[12:15]
	v_mfma_f32_16x16x32_bf16 v[16:19], v[170:173], v[186:189], v[16:19]
	v_mfma_f32_16x16x32_bf16 v[20:23], v[170:173], v[190:193], v[20:23]
	v_mfma_f32_16x16x32_bf16 v[24:27], v[174:177], v[178:181], v[24:27]
	v_mfma_f32_16x16x32_bf16 v[130:133], v[174:177], v[182:185], v[130:133]
	v_mfma_f32_16x16x32_bf16 v[134:137], v[174:177], v[186:189], v[134:137]
	v_mfma_f32_16x16x32_bf16 v[194:197], v[174:177], v[190:193], v[194:197]
	s_waitcnt vmcnt(12)
	ds_write_b128 v206, v[82:85]
	ds_write_b128 v206, v[86:89] offset:1152
	ds_write_b128 v206, v[90:93] offset:2304
	ds_write_b128 v206, v[94:97] offset:3456
	ds_write_b128 v206, v[98:101] offset:4608
	ds_write_b128 v206, v[102:105] offset:5760
	ds_write_b128 v206, v[106:109] offset:6912
	ds_write_b128 v207, v[110:113]
	ds_write_b128 v207, v[114:117] offset:1152
	ds_write_b128 v207, v[118:121] offset:2304
	ds_write_b128 v207, v[122:125] offset:3456
	ds_write_b128 v207, v[126:129] offset:4608
	global_load_dwordx4 v[82:85], v198, s[42:43] offset:640
	global_load_dwordx4 v[86:89], v199, s[42:43] offset:640
	global_load_dwordx4 v[90:93], v200, s[42:43] offset:640
	global_load_dwordx4 v[94:97], v201, s[42:43] offset:640
	global_load_dwordx4 v[98:101], v198, s[44:45] offset:640
	global_load_dwordx4 v[102:105], v199, s[44:45] offset:640
	global_load_dwordx4 v[106:109], v200, s[44:45] offset:640
	global_load_dwordx4 v[110:113], v201, s[44:45] offset:640
	global_load_dwordx4 v[114:117], v202, s[44:45] offset:640
	global_load_dwordx4 v[118:121], v203, s[44:45] offset:640
	global_load_dwordx4 v[122:125], v204, s[44:45] offset:640
	global_load_dwordx4 v[126:129], v205, s[44:45] offset:640
	ds_read_b128 v[146:149], v208 offset:0
	ds_read_b128 v[150:153], v208 offset:2304
	ds_read_b128 v[154:157], v208 offset:4608
	ds_read_b128 v[158:161], v226
	ds_read_b128 v[162:165], v209 offset:1152
	ds_read_b128 v[166:169], v209 offset:3456
	ds_read_b128 v[170:173], v208 offset:64
	ds_read_b128 v[174:177], v208 offset:2368
	ds_read_b128 v[178:181], v208 offset:4672
	ds_read_b128 v[182:185], v226 offset:64
	ds_read_b128 v[186:189], v209 offset:1216
	ds_read_b128 v[190:193], v209 offset:3520
	s_waitcnt lgkmcnt(6)
	v_mfma_f32_16x16x32_bf16 v[8:11], v[146:149], v[154:157], v[8:11]
	v_mfma_f32_16x16x32_bf16 v[12:15], v[146:149], v[158:161], v[12:15]
	v_mfma_f32_16x16x32_bf16 v[16:19], v[146:149], v[162:165], v[16:19]
	v_mfma_f32_16x16x32_bf16 v[20:23], v[146:149], v[166:169], v[20:23]
	v_mfma_f32_16x16x32_bf16 v[24:27], v[150:153], v[154:157], v[24:27]
	v_mfma_f32_16x16x32_bf16 v[130:133], v[150:153], v[158:161], v[130:133]
	v_mfma_f32_16x16x32_bf16 v[134:137], v[150:153], v[162:165], v[134:137]
	v_mfma_f32_16x16x32_bf16 v[194:197], v[150:153], v[166:169], v[194:197]
	s_waitcnt lgkmcnt(0)
	v_mfma_f32_16x16x32_bf16 v[8:11], v[170:173], v[178:181], v[8:11]
	v_mfma_f32_16x16x32_bf16 v[12:15], v[170:173], v[182:185], v[12:15]
	v_mfma_f32_16x16x32_bf16 v[16:19], v[170:173], v[186:189], v[16:19]
	v_mfma_f32_16x16x32_bf16 v[20:23], v[170:173], v[190:193], v[20:23]
	v_mfma_f32_16x16x32_bf16 v[24:27], v[174:177], v[178:181], v[24:27]
	v_mfma_f32_16x16x32_bf16 v[130:133], v[174:177], v[182:185], v[130:133]
	v_mfma_f32_16x16x32_bf16 v[134:137], v[174:177], v[186:189], v[134:137]
	v_mfma_f32_16x16x32_bf16 v[194:197], v[174:177], v[190:193], v[194:197]
	s_waitcnt vmcnt(12)
	ds_write_b128 v206, v[34:37]
	ds_write_b128 v206, v[38:41] offset:1152
	ds_write_b128 v206, v[42:45] offset:2304
	ds_write_b128 v206, v[46:49] offset:3456
	ds_write_b128 v206, v[50:53] offset:4608
	ds_write_b128 v206, v[54:57] offset:5760
	ds_write_b128 v206, v[58:61] offset:6912
	ds_write_b128 v207, v[62:65]
	ds_write_b128 v207, v[66:69] offset:1152
	ds_write_b128 v207, v[70:73] offset:2304
	ds_write_b128 v207, v[74:77] offset:3456
	ds_write_b128 v207, v[78:81] offset:4608
	global_load_dwordx4 v[34:37], v198, s[42:43] offset:768
	global_load_dwordx4 v[38:41], v199, s[42:43] offset:768
	global_load_dwordx4 v[42:45], v200, s[42:43] offset:768
	global_load_dwordx4 v[46:49], v201, s[42:43] offset:768
	global_load_dwordx4 v[50:53], v198, s[44:45] offset:768
	global_load_dwordx4 v[54:57], v199, s[44:45] offset:768
	global_load_dwordx4 v[58:61], v200, s[44:45] offset:768
	global_load_dwordx4 v[62:65], v201, s[44:45] offset:768
	global_load_dwordx4 v[66:69], v202, s[44:45] offset:768
	global_load_dwordx4 v[70:73], v203, s[44:45] offset:768
	global_load_dwordx4 v[74:77], v204, s[44:45] offset:768
	global_load_dwordx4 v[78:81], v205, s[44:45] offset:768
	ds_read_b128 v[146:149], v208 offset:0
	ds_read_b128 v[150:153], v208 offset:2304
	ds_read_b128 v[154:157], v208 offset:4608
	ds_read_b128 v[158:161], v226
	ds_read_b128 v[162:165], v209 offset:1152
	ds_read_b128 v[166:169], v209 offset:3456
	ds_read_b128 v[170:173], v208 offset:64
	ds_read_b128 v[174:177], v208 offset:2368
	ds_read_b128 v[178:181], v208 offset:4672
	ds_read_b128 v[182:185], v226 offset:64
	ds_read_b128 v[186:189], v209 offset:1216
	ds_read_b128 v[190:193], v209 offset:3520
	s_waitcnt lgkmcnt(6)
	v_mfma_f32_16x16x32_bf16 v[8:11], v[146:149], v[154:157], v[8:11]
	v_mfma_f32_16x16x32_bf16 v[12:15], v[146:149], v[158:161], v[12:15]
	v_mfma_f32_16x16x32_bf16 v[16:19], v[146:149], v[162:165], v[16:19]
	v_mfma_f32_16x16x32_bf16 v[20:23], v[146:149], v[166:169], v[20:23]
	v_mfma_f32_16x16x32_bf16 v[24:27], v[150:153], v[154:157], v[24:27]
	v_mfma_f32_16x16x32_bf16 v[130:133], v[150:153], v[158:161], v[130:133]
	v_mfma_f32_16x16x32_bf16 v[134:137], v[150:153], v[162:165], v[134:137]
	v_mfma_f32_16x16x32_bf16 v[194:197], v[150:153], v[166:169], v[194:197]
	s_waitcnt lgkmcnt(0)
; #define MFMA16(a, b, c) __builtin_amdgcn_mfma_f32_16x16x32_bf16((a), (b), (c), 0, 0, 0)
; __device__ __forceinline__ void sample_out_block(LAS unsigned char* lds, const bf16_t* A, const bf16_t* Bt, int K, bf16_t* xb, float* sspart, int blk, int tid) {
;     ...
;         for (int k0 = 0; k0 < kq; k0 += 64) {
;             const int k1 = (k0 + 64 < kq) ? k0 + 64 : k0;
; #pragma unroll
;             for (int s = 0; s < 2; ++s) {
; #pragma unroll
;                 for (int ra = 0; ra < 2; ++ra) afn[s][ra] = *(const bf16x8*)(ap + (size_t)(16 * ra) * K + k1 + 32 * s);
; #pragma unroll
;                 for (int nt = 0; nt < 4; ++nt) bfn[s][nt] = *(const bf16x8*)(bp + (size_t)(16 * nt) * K + k1 + 32 * s);
;             }
; #pragma unroll
;             for (int s = 0; s < 2; ++s)
; #pragma unroll
;                 for (int ra = 0; ra < 2; ++ra)
; #pragma unroll
;                     for (int nt = 0; nt < 4; ++nt) acc[ra][nt] = MFMA16(af[s][ra], bf[s][nt], acc[ra][nt]);
; #pragma unroll
;             for (int s = 0; s < 2; ++s) {
; #pragma unroll
;                 for (int ra = 0; ra < 2; ++ra) af[s][ra] = afn[s][ra];
; #pragma unroll
;                 for (int nt = 0; nt < 4; ++nt) bf[s][nt] = bfn[s][nt];
;             }
;         }
	v_mfma_f32_16x16x32_bf16 v[8:11], v[170:173], v[178:181], v[8:11]
	v_mfma_f32_16x16x32_bf16 v[12:15], v[170:173], v[182:185], v[12:15]
	v_mfma_f32_16x16x32_bf16 v[16:19], v[170:173], v[186:189], v[16:19]
	v_mfma_f32_16x16x32_bf16 v[20:23], v[170:173], v[190:193], v[20:23]
	v_mfma_f32_16x16x32_bf16 v[24:27], v[174:177], v[178:181], v[24:27]
	v_mfma_f32_16x16x32_bf16 v[130:133], v[174:177], v[182:185], v[130:133]
	v_mfma_f32_16x16x32_bf16 v[134:137], v[174:177], v[186:189], v[134:137]
	v_mfma_f32_16x16x32_bf16 v[194:197], v[174:177], v[190:193], v[194:197]
	s_waitcnt vmcnt(12)
	ds_write_b128 v206, v[82:85]
	ds_write_b128 v206, v[86:89] offset:1152
	ds_write_b128 v206, v[90:93] offset:2304
	ds_write_b128 v206, v[94:97] offset:3456
	ds_write_b128 v206, v[98:101] offset:4608
	ds_write_b128 v206, v[102:105] offset:5760
	ds_write_b128 v206, v[106:109] offset:6912
	ds_write_b128 v207, v[110:113]
	ds_write_b128 v207, v[114:117] offset:1152
	ds_write_b128 v207, v[118:121] offset:2304
	ds_write_b128 v207, v[122:125] offset:3456
	ds_write_b128 v207, v[126:129] offset:4608
	global_load_dwordx4 v[82:85], v198, s[42:43] offset:896
	global_load_dwordx4 v[86:89], v199, s[42:43] offset:896
	global_load_dwordx4 v[90:93], v200, s[42:43] offset:896
	global_load_dwordx4 v[94:97], v201, s[42:43] offset:896
	global_load_dwordx4 v[98:101], v198, s[44:45] offset:896
	global_load_dwordx4 v[102:105], v199, s[44:45] offset:896
	global_load_dwordx4 v[106:109], v200, s[44:45] offset:896
	global_load_dwordx4 v[110:113], v201, s[44:45] offset:896
	global_load_dwordx4 v[114:117], v202, s[44:45] offset:896
	global_load_dwordx4 v[118:121], v203, s[44:45] offset:896
	global_load_dwordx4 v[122:125], v204, s[44:45] offset:896
	global_load_dwordx4 v[126:129], v205, s[44:45] offset:896
	ds_read_b128 v[146:149], v208 offset:0
	ds_read_b128 v[150:153], v208 offset:2304
	ds_read_b128 v[154:157], v208 offset:4608
	ds_read_b128 v[158:161], v226
	ds_read_b128 v[162:165], v209 offset:1152
	ds_read_b128 v[166:169], v209 offset:3456
	ds_read_b128 v[170:173], v208 offset:64
	ds_read_b128 v[174:177], v208 offset:2368
	ds_read_b128 v[178:181], v208 offset:4672
	ds_read_b128 v[182:185], v226 offset:64
	ds_read_b128 v[186:189], v209 offset:1216
	ds_read_b128 v[190:193], v209 offset:3520
	s_waitcnt lgkmcnt(6)
	v_mfma_f32_16x16x32_bf16 v[8:11], v[146:149], v[154:157], v[8:11]
	v_mfma_f32_16x16x32_bf16 v[12:15], v[146:149], v[158:161], v[12:15]
	v_mfma_f32_16x16x32_bf16 v[16:19], v[146:149], v[162:165], v[16:19]
	v_mfma_f32_16x16x32_bf16 v[20:23], v[146:149], v[166:169], v[20:23]
	v_mfma_f32_16x16x32_bf16 v[24:27], v[150:153], v[154:157], v[24:27]
	v_mfma_f32_16x16x32_bf16 v[130:133], v[150:153], v[158:161], v[130:133]
	v_mfma_f32_16x16x32_bf16 v[134:137], v[150:153], v[162:165], v[134:137]
	v_mfma_f32_16x16x32_bf16 v[194:197], v[150:153], v[166:169], v[194:197]
	s_waitcnt lgkmcnt(0)
	v_mfma_f32_16x16x32_bf16 v[8:11], v[170:173], v[178:181], v[8:11]
	v_mfma_f32_16x16x32_bf16 v[12:15], v[170:173], v[182:185], v[12:15]
	v_mfma_f32_16x16x32_bf16 v[16:19], v[170:173], v[186:189], v[16:19]
	v_mfma_f32_16x16x32_bf16 v[20:23], v[170:173], v[190:193], v[20:23]
	v_mfma_f32_16x16x32_bf16 v[24:27], v[174:177], v[178:181], v[24:27]
	v_mfma_f32_16x16x32_bf16 v[130:133], v[174:177], v[182:185], v[130:133]
	v_mfma_f32_16x16x32_bf16 v[134:137], v[174:177], v[186:189], v[134:137]
	v_mfma_f32_16x16x32_bf16 v[194:197], v[174:177], v[190:193], v[194:197]
	s_waitcnt vmcnt(12)
	ds_write_b128 v206, v[34:37]
	ds_write_b128 v206, v[38:41] offset:1152
	ds_write_b128 v206, v[42:45] offset:2304
	ds_write_b128 v206, v[46:49] offset:3456
	ds_write_b128 v206, v[50:53] offset:4608
	ds_write_b128 v206, v[54:57] offset:5760
	ds_write_b128 v206, v[58:61] offset:6912
	ds_write_b128 v207, v[62:65]
	ds_write_b128 v207, v[66:69] offset:1152
	ds_write_b128 v207, v[70:73] offset:2304
	ds_write_b128 v207, v[74:77] offset:3456
	ds_write_b128 v207, v[78:81] offset:4608
	ds_read_b128 v[146:149], v208 offset:0
	ds_read_b128 v[150:153], v208 offset:2304
	ds_read_b128 v[154:157], v208 offset:4608
	ds_read_b128 v[158:161], v226
	ds_read_b128 v[162:165], v209 offset:1152
	ds_read_b128 v[166:169], v209 offset:3456
	ds_read_b128 v[170:173], v208 offset:64
	ds_read_b128 v[174:177], v208 offset:2368
	ds_read_b128 v[178:181], v208 offset:4672
	ds_read_b128 v[182:185], v226 offset:64
	ds_read_b128 v[186:189], v209 offset:1216
	ds_read_b128 v[190:193], v209 offset:3520
	s_waitcnt lgkmcnt(6)
	v_mfma_f32_16x16x32_bf16 v[8:11], v[146:149], v[154:157], v[8:11]
	v_mfma_f32_16x16x32_bf16 v[12:15], v[146:149], v[158:161], v[12:15]
	v_mfma_f32_16x16x32_bf16 v[16:19], v[146:149], v[162:165], v[16:19]
	v_mfma_f32_16x16x32_bf16 v[20:23], v[146:149], v[166:169], v[20:23]
	v_mfma_f32_16x16x32_bf16 v[24:27], v[150:153], v[154:157], v[24:27]
	v_mfma_f32_16x16x32_bf16 v[130:133], v[150:153], v[158:161], v[130:133]
	v_mfma_f32_16x16x32_bf16 v[134:137], v[150:153], v[162:165], v[134:137]
	v_mfma_f32_16x16x32_bf16 v[194:197], v[150:153], v[166:169], v[194:197]
	s_waitcnt lgkmcnt(0)
	v_mfma_f32_16x16x32_bf16 v[8:11], v[170:173], v[178:181], v[8:11]
	v_mfma_f32_16x16x32_bf16 v[12:15], v[170:173], v[182:185], v[12:15]
	v_mfma_f32_16x16x32_bf16 v[16:19], v[170:173], v[186:189], v[16:19]
	v_mfma_f32_16x16x32_bf16 v[20:23], v[170:173], v[190:193], v[20:23]
	v_mfma_f32_16x16x32_bf16 v[24:27], v[174:177], v[178:181], v[24:27]
	v_mfma_f32_16x16x32_bf16 v[130:133], v[174:177], v[182:185], v[130:133]
	v_mfma_f32_16x16x32_bf16 v[134:137], v[174:177], v[186:189], v[134:137]
	v_mfma_f32_16x16x32_bf16 v[194:197], v[174:177], v[190:193], v[194:197]
	s_waitcnt vmcnt(0)
; #define LAS __attribute__((address_space(3)))
; #define MFMA16(a, b, c) __builtin_amdgcn_mfma_f32_16x16x32_bf16((a), (b), (c), 0, 0, 0)
; __device__ __forceinline__ float bf1(bf16_t h) { return __uint_as_float((unsigned)h << 16); }
; __device__ __forceinline__ bf16_t f2bf(float f) { return (bf16_t)(pk2(f, 0.f) & 0xffffu); }
; __device__ __forceinline__ void sample_out_block(LAS unsigned char* lds, const bf16_t* A, const bf16_t* Bt, int K, bf16_t* xb, float* sspart, int blk, int tid) {
;     ...
; #pragma unroll
;             for (int s = 0; s < 2; ++s)
; #pragma unroll
;                 for (int ra = 0; ra < 2; ++ra)
; #pragma unroll
;                     for (int nt = 0; nt < 4; ++nt) acc[ra][nt] = MFMA16(af[s][ra], bf[s][nt], acc[ra][nt]);
; #pragma unroll
;             for (int s = 0; s < 2; ++s) {
; #pragma unroll
;                 for (int ra = 0; ra < 2; ++ra) af[s][ra] = afn[s][ra];
; #pragma unroll
;                 for (int nt = 0; nt < 4; ++nt) bf[s][nt] = bfn[s][nt];
;             }
;         }
;     }
;     LAS f32x4* part = (LAS f32x4*)lds;
; #pragma unroll
;     for (int ra = 0; ra < 2; ++ra)
; #pragma unroll
;         for (int nt = 0; nt < 4; ++nt) part[(wave * 8 + ra * 4 + nt) * 64 + lane] = acc[ra][nt];
;     __syncthreads();
;     if (wave < 2) {
;         const int ra = wave;
;         f32x4 sum[4];
; #pragma unroll
;         for (int nt = 0; nt < 4; ++nt) {
;             sum[nt] = part[(0 * 8 + ra * 4 + nt) * 64 + lane];
; #pragma unroll
;             for (int w = 1; w < 8; ++w) sum[nt] += part[(w * 8 + ra * 4 + nt) * 64 + lane];
;         }
;         float ss[4] = {0.f, 0.f, 0.f, 0.f};
; #pragma unroll
;         for (int j = 0; j < 4; ++j)
; #pragma unroll
;             for (int nt = 0; nt < 4; ++nt) {
;                 bf16_t* xp = xb + (size_t)(r0 + 16 * ra + 4 * g + j) * 2048 + 64 * cg + 16 * nt + l15;
;                 const bf16_t nv = f2bf(bf1(*xp) + sum[nt][j]);
;                 *xp = nv; const float r = bf1(nv); ss[j] += r * r;
	ds_write_b128 v206, v[82:85]
	ds_write_b128 v206, v[86:89] offset:1152
	ds_write_b128 v206, v[90:93] offset:2304
	ds_write_b128 v206, v[94:97] offset:3456
	ds_write_b128 v206, v[98:101] offset:4608
	ds_write_b128 v206, v[102:105] offset:5760
	ds_write_b128 v206, v[106:109] offset:6912
	ds_write_b128 v207, v[110:113]
	ds_write_b128 v207, v[114:117] offset:1152
	ds_write_b128 v207, v[118:121] offset:2304
	ds_write_b128 v207, v[122:125] offset:3456
	ds_write_b128 v207, v[126:129] offset:4608
	ds_read_b128 v[146:149], v208 offset:0
	ds_read_b128 v[150:153], v208 offset:2304
	ds_read_b128 v[154:157], v208 offset:4608
	ds_read_b128 v[158:161], v226
	ds_read_b128 v[162:165], v209 offset:1152
	ds_read_b128 v[166:169], v209 offset:3456
	ds_read_b128 v[170:173], v208 offset:64
	ds_read_b128 v[174:177], v208 offset:2368
	ds_read_b128 v[178:181], v208 offset:4672
	ds_read_b128 v[182:185], v226 offset:64
	ds_read_b128 v[186:189], v209 offset:1216
	ds_read_b128 v[190:193], v209 offset:3520
	s_waitcnt lgkmcnt(6)
	v_mfma_f32_16x16x32_bf16 v[8:11], v[146:149], v[154:157], v[8:11]
	v_mfma_f32_16x16x32_bf16 v[12:15], v[146:149], v[158:161], v[12:15]
	v_mfma_f32_16x16x32_bf16 v[16:19], v[146:149], v[162:165], v[16:19]
	v_mfma_f32_16x16x32_bf16 v[20:23], v[146:149], v[166:169], v[20:23]
	v_mfma_f32_16x16x32_bf16 v[24:27], v[150:153], v[154:157], v[24:27]
	v_mfma_f32_16x16x32_bf16 v[130:133], v[150:153], v[158:161], v[130:133]
	v_mfma_f32_16x16x32_bf16 v[134:137], v[150:153], v[162:165], v[134:137]
	v_mfma_f32_16x16x32_bf16 v[194:197], v[150:153], v[166:169], v[194:197]
	s_waitcnt lgkmcnt(0)
	v_mfma_f32_16x16x32_bf16 v[8:11], v[170:173], v[178:181], v[8:11]
	v_mfma_f32_16x16x32_bf16 v[12:15], v[170:173], v[182:185], v[12:15]
	v_mfma_f32_16x16x32_bf16 v[16:19], v[170:173], v[186:189], v[16:19]
	v_mfma_f32_16x16x32_bf16 v[20:23], v[170:173], v[190:193], v[20:23]
	v_mfma_f32_16x16x32_bf16 v[24:27], v[174:177], v[178:181], v[24:27]
	v_mfma_f32_16x16x32_bf16 v[130:133], v[174:177], v[182:185], v[130:133]
	v_mfma_f32_16x16x32_bf16 v[134:137], v[174:177], v[186:189], v[134:137]
	v_mfma_f32_16x16x32_bf16 v[194:197], v[174:177], v[190:193], v[194:197]
	s_nop 7
	s_nop 7
	ds_write_b128 v32, v[8:11]
	ds_write_b128 v32, v[12:15] offset:1024
	ds_write_b128 v32, v[16:19] offset:2048
	ds_write_b128 v32, v[20:23] offset:3072
	ds_write_b128 v32, v[24:27] offset:4096
	ds_write_b128 v32, v[130:133] offset:5120
	ds_write_b128 v32, v[134:137] offset:6144
	ds_write_b128 v32, v[194:197] offset:7168
	s_waitcnt lgkmcnt(0)
	s_barrier
	s_and_saveexec_b64 s[10:11], s[6:7]
	s_cbranch_execz .LBB0_541
	v_add_u32_e32 v170, s27, v31
	v_lshlrev_b32_e32 v170, 12, v170
	s_lshl_b32 s36, s35, 1
	v_add_u32_e32 v170, s36, v170
	v_mov_b32_e32 v171, 0
	s_mov_b64 s[38:39], 0x1000
	v_lshl_add_u64 v[162:163], v[6:7], 0, v[170:171]
	v_lshl_add_u64 v[164:165], v[162:163], 0, s[38:39]
	v_lshl_add_u64 v[166:167], v[164:165], 0, s[38:39]
	v_lshl_add_u64 v[168:169], v[166:167], 0, s[38:39]
	global_load_ushort v146, v[162:163], off
	global_load_ushort v147, v[162:163], off offset:32
	global_load_ushort v148, v[162:163], off offset:64
	global_load_ushort v149, v[162:163], off offset:96
	global_load_ushort v150, v[164:165], off
	global_load_ushort v151, v[164:165], off offset:32
	global_load_ushort v152, v[164:165], off offset:64
	global_load_ushort v153, v[164:165], off offset:96
	global_load_ushort v154, v[166:167], off
	global_load_ushort v155, v[166:167], off offset:32
	global_load_ushort v156, v[166:167], off offset:64
	global_load_ushort v157, v[166:167], off offset:96
	global_load_ushort v158, v[168:169], off
	global_load_ushort v159, v[168:169], off offset:32
	global_load_ushort v160, v[168:169], off offset:64
	global_load_ushort v161, v[168:169], off offset:96
	ds_read_b128 v[8:11], v33
	ds_read_b128 v[12:15], v33 offset:8192
	s_lshl_b32 s80, s35, 1
	v_lshl_add_u64 v[28:29], v[6:7], 0, s[80:81]
	s_lshl_b32 s12, s26, 2
	s_add_u32 s12, s22, s12
	s_waitcnt lgkmcnt(0)
	v_pk_add_f32 v[14:15], v[10:11], v[14:15]
	v_pk_add_f32 v[12:13], v[8:9], v[12:13]
	ds_read_b128 v[8:11], v33 offset:16384
	s_addc_u32 s13, s23, 0
	s_waitcnt lgkmcnt(0)
	v_pk_add_f32 v[14:15], v[14:15], v[10:11]
	v_pk_add_f32 v[12:13], v[12:13], v[8:9]
	ds_read_b128 v[8:11], v33 offset:24576
	s_waitcnt lgkmcnt(0)
	v_pk_add_f32 v[14:15], v[14:15], v[10:11]
	v_pk_add_f32 v[12:13], v[12:13], v[8:9]
	ds_read_b128 v[8:11], v33 offset:32768
	s_waitcnt lgkmcnt(0)
	v_pk_add_f32 v[14:15], v[14:15], v[10:11]
	v_pk_add_f32 v[12:13], v[12:13], v[8:9]
	ds_read_b128 v[8:11], v33 offset:40960
	s_waitcnt lgkmcnt(0)
	v_pk_add_f32 v[14:15], v[14:15], v[10:11]
	v_pk_add_f32 v[12:13], v[12:13], v[8:9]
	ds_read_b128 v[8:11], v33 offset:49152
	s_waitcnt lgkmcnt(0)
	v_pk_add_f32 v[14:15], v[14:15], v[10:11]
	v_pk_add_f32 v[16:17], v[12:13], v[8:9]
	ds_read_b128 v[8:11], v33 offset:57344
	s_waitcnt lgkmcnt(0)
	v_pk_add_f32 v[12:13], v[14:15], v[10:11]
	v_pk_add_f32 v[20:21], v[16:17], v[8:9]
	ds_read_b128 v[8:11], v33 offset:1024
	ds_read_b128 v[14:17], v33 offset:9216
	s_waitcnt lgkmcnt(0)
	v_pk_add_f32 v[16:17], v[10:11], v[16:17]
	v_pk_add_f32 v[14:15], v[8:9], v[14:15]
	ds_read_b128 v[8:11], v33 offset:17408
	s_waitcnt lgkmcnt(0)
	v_pk_add_f32 v[16:17], v[16:17], v[10:11]
	v_pk_add_f32 v[14:15], v[14:15], v[8:9]
	ds_read_b128 v[8:11], v33 offset:25600
	s_waitcnt lgkmcnt(0)
	v_pk_add_f32 v[16:17], v[16:17], v[10:11]
	v_pk_add_f32 v[14:15], v[14:15], v[8:9]
	ds_read_b128 v[8:11], v33 offset:33792
	s_waitcnt lgkmcnt(0)
	v_pk_add_f32 v[16:17], v[16:17], v[10:11]
	v_pk_add_f32 v[14:15], v[14:15], v[8:9]
	ds_read_b128 v[8:11], v33 offset:41984
	s_waitcnt lgkmcnt(0)
; __device__ __forceinline__ float bf1(bf16_t h) { return __uint_as_float((unsigned)h << 16); }
; __device__ __forceinline__ bf16_t f2bf(float f) { return (bf16_t)(pk2(f, 0.f) & 0xffffu); }
; __device__ __forceinline__ void sample_out_block(LAS unsigned char* lds, const bf16_t* A, const bf16_t* Bt, int K, bf16_t* xb, float* sspart, int blk, int tid) {
;     ...
;         const int ra = wave;
;         f32x4 sum[4];
; #pragma unroll
;         for (int nt = 0; nt < 4; ++nt) {
;             sum[nt] = part[(0 * 8 + ra * 4 + nt) * 64 + lane];
; #pragma unroll
;             for (int w = 1; w < 8; ++w) sum[nt] += part[(w * 8 + ra * 4 + nt) * 64 + lane];
;         }
;         float ss[4] = {0.f, 0.f, 0.f, 0.f};
; #pragma unroll
;         for (int j = 0; j < 4; ++j)
; #pragma unroll
;             for (int nt = 0; nt < 4; ++nt) {
;                 bf16_t* xp = xb + (size_t)(r0 + 16 * ra + 4 * g + j) * 2048 + 64 * cg + 16 * nt + l15;
;                 const bf16_t nv = f2bf(bf1(*xp) + sum[nt][j]);
;                 *xp = nv; const float r = bf1(nv); ss[j] += r * r;
;             }
; #pragma unroll
;         for (int j = 0; j < 4; ++j) {
;             float s = ss[j];
;             s += __shfl_xor(s, 1); s += __shfl_xor(s, 2); s += __shfl_xor(s, 4); s += __shfl_xor(s, 8);
;             if (l15 == 0) sspart[(size_t)(r0 + 16 * ra + 4 * g + j) * 32 + cg] = s;
	v_pk_add_f32 v[16:17], v[16:17], v[10:11]
	v_pk_add_f32 v[14:15], v[14:15], v[8:9]
	ds_read_b128 v[8:11], v33 offset:50176
	s_waitcnt lgkmcnt(0)
	v_pk_add_f32 v[16:17], v[16:17], v[10:11]
	v_pk_add_f32 v[14:15], v[14:15], v[8:9]
	ds_read_b128 v[8:11], v33 offset:58368
	s_waitcnt lgkmcnt(0)
	v_pk_add_f32 v[18:19], v[16:17], v[10:11]
	v_pk_add_f32 v[26:27], v[14:15], v[8:9]
	ds_read_b128 v[8:11], v33 offset:2048
	ds_read_b128 v[14:17], v33 offset:10240
	s_waitcnt lgkmcnt(0)
	v_pk_add_f32 v[16:17], v[10:11], v[16:17]
	v_pk_add_f32 v[14:15], v[8:9], v[14:15]
	ds_read_b128 v[8:11], v33 offset:18432
	s_waitcnt lgkmcnt(0)
	v_pk_add_f32 v[16:17], v[16:17], v[10:11]
	v_pk_add_f32 v[14:15], v[14:15], v[8:9]
	ds_read_b128 v[8:11], v33 offset:26624
	s_waitcnt lgkmcnt(0)
	v_pk_add_f32 v[16:17], v[16:17], v[10:11]
	v_pk_add_f32 v[14:15], v[14:15], v[8:9]
	ds_read_b128 v[8:11], v33 offset:34816
	s_waitcnt lgkmcnt(0)
	v_pk_add_f32 v[16:17], v[16:17], v[10:11]
	v_pk_add_f32 v[14:15], v[14:15], v[8:9]
	ds_read_b128 v[8:11], v33 offset:43008
	s_waitcnt lgkmcnt(0)
	v_pk_add_f32 v[16:17], v[16:17], v[10:11]
	v_pk_add_f32 v[14:15], v[14:15], v[8:9]
	ds_read_b128 v[8:11], v33 offset:51200
	s_waitcnt lgkmcnt(0)
	v_pk_add_f32 v[16:17], v[16:17], v[10:11]
	v_pk_add_f32 v[14:15], v[14:15], v[8:9]
	ds_read_b128 v[8:11], v33 offset:59392
	s_waitcnt lgkmcnt(0)
	v_pk_add_f32 v[16:17], v[16:17], v[10:11]
	v_pk_add_f32 v[24:25], v[14:15], v[8:9]
	ds_read_b128 v[8:11], v33 offset:3072
	ds_read_b128 v[34:37], v33 offset:11264
	s_waitcnt lgkmcnt(0)
	v_pk_add_f32 v[14:15], v[10:11], v[36:37]
	v_pk_add_f32 v[22:23], v[8:9], v[34:35]
	ds_read_b128 v[8:11], v33 offset:19456
	ds_read_b128 v[34:37], v33 offset:60416
	s_waitcnt lgkmcnt(1)
	v_pk_add_f32 v[14:15], v[14:15], v[10:11]
	v_pk_add_f32 v[22:23], v[22:23], v[8:9]
	ds_read_b128 v[8:11], v33 offset:27648
	s_waitcnt lgkmcnt(0)
	v_pk_add_f32 v[14:15], v[14:15], v[10:11]
	v_pk_add_f32 v[22:23], v[22:23], v[8:9]
	ds_read_b128 v[8:11], v33 offset:35840
	s_waitcnt lgkmcnt(0)
	v_pk_add_f32 v[14:15], v[14:15], v[10:11]
	v_pk_add_f32 v[22:23], v[22:23], v[8:9]
	ds_read_b128 v[8:11], v33 offset:44032
	s_waitcnt lgkmcnt(0)
	v_pk_add_f32 v[14:15], v[14:15], v[10:11]
	v_pk_add_f32 v[22:23], v[22:23], v[8:9]
	ds_read_b128 v[8:11], v33 offset:52224
	s_waitcnt lgkmcnt(0)
	v_pk_add_f32 v[10:11], v[14:15], v[10:11]
	v_pk_add_f32 v[14:15], v[22:23], v[8:9]
	v_pk_add_f32 v[8:9], v[10:11], v[36:37]
	v_add_u32_e32 v10, s27, v31
	v_ashrrev_i32_e32 v11, 31, v10
	v_pk_add_f32 v[22:23], v[14:15], v[34:35]
	v_lshlrev_b64 v[14:15], 12, v[10:11]
	v_lshl_add_u64 v[14:15], v[28:29], 0, v[14:15]
	s_waitcnt vmcnt(0)
	v_mov_b32_e32 v0, v146
	v_lshlrev_b32_e32 v0, 16, v0
	v_add_f32_e32 v0, v20, v0
	v_cvt_pk_bf16_f32 v0, v0, s0
	global_store_short v[14:15], v0, off
	v_lshlrev_b32_e32 v20, 16, v0
	v_mov_b32_e32 v0, v147
	v_lshlrev_b32_e32 v0, 16, v0
	v_add_f32_e32 v0, v26, v0
	v_cvt_pk_bf16_f32 v0, v0, s0
	global_store_short v[14:15], v0, off offset:32
	v_lshlrev_b32_e32 v0, 16, v0
	v_mul_f32_e32 v0, v0, v0
	v_fmac_f32_e32 v0, v20, v20
	v_mov_b32_e32 v20, v148
	v_lshlrev_b32_e32 v20, 16, v20
	v_add_f32_e32 v20, v24, v20
	v_cvt_pk_bf16_f32 v20, v20, s0
	global_store_short v[14:15], v20, off offset:64
	v_lshlrev_b32_e32 v20, 16, v20
	v_fmac_f32_e32 v0, v20, v20
	v_mov_b32_e32 v20, v149
	v_lshlrev_b32_e32 v20, 16, v20
	v_add_f32_e32 v20, v22, v20
	v_cvt_pk_bf16_f32 v20, v20, s0
	global_store_short v[14:15], v20, off offset:96
	v_lshlrev_b32_e32 v14, 16, v20
	v_fmac_f32_e32 v0, v14, v14
	v_or_b32_e32 v14, 1, v10
	v_ashrrev_i32_e32 v15, 31, v14
	v_lshlrev_b64 v[34:35], 12, v[14:15]
	v_lshl_add_u64 v[36:37], v[28:29], 0, v[34:35]
	v_mov_b32_e32 v20, v150
	v_lshlrev_b32_e32 v20, 16, v20
	v_add_f32_e32 v20, v21, v20
	v_cvt_pk_bf16_f32 v26, v20, s0
	v_mov_b32_e32 v20, v151
	v_lshlrev_b32_e32 v20, 16, v20
	v_add_f32_e32 v20, v27, v20
	v_cvt_pk_bf16_f32 v27, v20, s0
	v_mov_b32_e32 v20, v152
	v_lshlrev_b32_e32 v20, 16, v20
	v_add_f32_e32 v20, v25, v20
	v_cvt_pk_bf16_f32 v34, v20, s0
	v_mov_b32_e32 v20, v153
	v_lshlrev_b32_e32 v20, 16, v20
	v_add_f32_e32 v20, v23, v20
	v_cvt_pk_bf16_f32 v35, v20, s0
	v_or_b32_e32 v20, 2, v10
	v_ashrrev_i32_e32 v21, 31, v20
	v_lshlrev_b64 v[22:23], 12, v[20:21]
	v_lshl_add_u64 v[22:23], v[28:29], 0, v[22:23]
	v_mov_b32_e32 v24, v154
	v_lshlrev_b32_e32 v24, 16, v24
	v_add_f32_e32 v12, v12, v24
	v_mov_b32_e32 v24, v155
	v_cvt_pk_bf16_f32 v12, v12, s0
	global_store_short v[22:23], v12, off
	global_store_short v[36:37], v26, off
	global_store_short v[36:37], v27, off offset:32
	global_store_short v[36:37], v34, off offset:64
	global_store_short v[36:37], v35, off offset:96
	v_xor_b32_e32 v36, 8, v215
	s_waitcnt vmcnt(5)
	v_lshlrev_b32_e32 v24, 16, v24
	v_add_f32_e32 v18, v18, v24
	v_mov_b32_e32 v24, v156
	v_cvt_pk_bf16_f32 v18, v18, s0
	global_store_short v[22:23], v18, off offset:32
	s_waitcnt vmcnt(1)
	v_lshlrev_b32_e32 v24, 16, v24
	v_add_f32_e32 v16, v16, v24
	v_mov_b32_e32 v24, v157
	v_cvt_pk_bf16_f32 v16, v16, s0
	global_store_short v[22:23], v16, off offset:64
	s_waitcnt vmcnt(1)
	v_lshlrev_b32_e32 v24, 16, v24
	v_add_f32_e32 v8, v8, v24
	v_cvt_pk_bf16_f32 v8, v8, s0
	global_store_short v[22:23], v8, off offset:96
	v_or_b32_e32 v22, 3, v10
	v_ashrrev_i32_e32 v23, 31, v22
	v_lshlrev_b64 v[24:25], 12, v[22:23]
	v_lshl_add_u64 v[24:25], v[28:29], 0, v[24:25]
	v_mov_b32_e32 v28, v158
	v_lshlrev_b32_e32 v28, 16, v28
	v_add_f32_e32 v13, v13, v28
	v_mov_b32_e32 v28, v159
	v_cvt_pk_bf16_f32 v13, v13, s0
	global_store_short v[24:25], v13, off
	s_waitcnt vmcnt(1)
	v_lshlrev_b32_e32 v28, 16, v28
	v_add_f32_e32 v19, v19, v28
	v_mov_b32_e32 v28, v160
	v_cvt_pk_bf16_f32 v19, v19, s0
	global_store_short v[24:25], v19, off offset:32
	s_waitcnt vmcnt(1)
	v_lshlrev_b32_e32 v28, 16, v28
	v_add_f32_e32 v17, v17, v28
	v_mov_b32_e32 v28, v161
	v_cvt_pk_bf16_f32 v17, v17, s0
	global_store_short v[24:25], v17, off offset:64
	s_waitcnt vmcnt(1)
	v_lshlrev_b32_e32 v28, 16, v28
	v_add_f32_e32 v9, v9, v28
	v_cvt_pk_bf16_f32 v9, v9, s0
	global_store_short v[24:25], v9, off offset:96
	v_and_b32_e32 v25, 64, v215
	v_xor_b32_e32 v24, 1, v215
	v_add_u32_e32 v29, 64, v25
	v_cmp_lt_i32_e32 vcc, v24, v29
	v_xor_b32_e32 v25, 2, v215
	v_xor_b32_e32 v28, 4, v215
	v_cndmask_b32_e32 v24, v215, v24, vcc
	v_cmp_lt_i32_e32 vcc, v25, v29
	v_lshlrev_b32_e32 v24, 2, v24
	s_nop 0
	v_cndmask_b32_e32 v25, v215, v25, vcc
	v_cmp_lt_i32_e32 vcc, v28, v29
	v_lshlrev_b32_e32 v25, 2, v25
	s_nop 0
	v_cndmask_b32_e32 v28, v215, v28, vcc
	v_cmp_lt_i32_e32 vcc, v36, v29
	v_lshlrev_b32_e32 v28, 2, v28
	s_nop 0
	v_cndmask_b32_e32 v29, v215, v36, vcc
	ds_bpermute_b32 v36, v24, v0
	v_lshlrev_b32_e32 v29, 2, v29
	s_waitcnt lgkmcnt(0)
	v_add_f32_e32 v0, v0, v36
	ds_bpermute_b32 v36, v25, v0
	s_waitcnt lgkmcnt(0)
	v_add_f32_e32 v0, v0, v36
	ds_bpermute_b32 v36, v28, v0
	s_waitcnt lgkmcnt(0)
	v_add_f32_e32 v0, v0, v36
	ds_bpermute_b32 v36, v29, v0
	s_and_saveexec_b64 s[26:27], s[8:9]
	s_cbranch_execz .LBB0_545
; __device__ __forceinline__ void sample_out_block(LAS unsigned char* lds, const bf16_t* A, const bf16_t* Bt, int K, bf16_t* xb, float* sspart, int blk, int tid) {
;     ...
;         for (int j = 0; j < 4; ++j) {
;             float s = ss[j];
;             s += __shfl_xor(s, 1); s += __shfl_xor(s, 2); s += __shfl_xor(s, 4); s += __shfl_xor(s, 8);
;             if (l15 == 0) sspart[(size_t)(r0 + 16 * ra + 4 * g + j) * 32 + cg] = s;
;         }
	v_lshlrev_b64 v[10:11], 7, v[10:11]
	v_lshl_add_u64 v[10:11], s[12:13], 0, v[10:11]
	s_waitcnt lgkmcnt(0)
	v_add_f32_e32 v0, v0, v36
	global_store_dword v[10:11], v0, off

; #define MFMA16(a, b, c) __builtin_amdgcn_mfma_f32_16x16x32_bf16((a), (b), (c), 0, 0, 0)
; __device__ __forceinline__ void sample_out_block(LAS unsigned char* lds, const bf16_t* A, const bf16_t* Bt, int K, bf16_t* xb, float* sspart, int blk, int tid) {
;     const int wave = tid >> 6, lane = tid & 63, l15 = lane & 15, g = lane >> 4;
;     const int rt = blk >> 5, cg = blk & 31, r0 = T_P + 32 * rt;
;     const int kq = K >> 3;
;     f32x4 acc[2][4];
; #pragma unroll
;     for (int ra = 0; ra < 2; ++ra)
; #pragma unroll
;         for (int nt = 0; nt < 4; ++nt) acc[ra][nt] = (f32x4){0.f, 0.f, 0.f, 0.f};
;     {
;         const bf16_t* ap = A + (size_t)(r0 + l15) * K + wave * kq + 8 * g;
;         const bf16_t* bp = Bt + (size_t)(64 * cg + l15) * K + wave * kq + 8 * g;
;         bf16x8 af[2][2], bf[2][4], afn[2][2], bfn[2][4];
; #pragma unroll
;         for (int s = 0; s < 2; ++s) {
; #pragma unroll
;             for (int ra = 0; ra < 2; ++ra) af[s][ra] = *(const bf16x8*)(ap + (size_t)(16 * ra) * K + 32 * s);
; #pragma unroll
;             for (int nt = 0; nt < 4; ++nt) bf[s][nt] = *(const bf16x8*)(bp + (size_t)(16 * nt) * K + 32 * s);
;         }
;         for (int k0 = 0; k0 < kq; k0 += 64) {
;             const int k1 = (k0 + 64 < kq) ? k0 + 64 : k0;
; #pragma unroll
;             for (int s = 0; s < 2; ++s) {
; #pragma unroll
;                 for (int ra = 0; ra < 2; ++ra) afn[s][ra] = *(const bf16x8*)(ap + (size_t)(16 * ra) * K + k1 + 32 * s);
; #pragma unroll
;                 for (int nt = 0; nt < 4; ++nt) bfn[s][nt] = *(const bf16x8*)(bp + (size_t)(16 * nt) * K + k1 + 32 * s);
;             }
; #pragma unroll
;             for (int s = 0; s < 2; ++s)
; #pragma unroll
;                 for (int ra = 0; ra < 2; ++ra)
; #pragma unroll
;                     for (int nt = 0; nt < 4; ++nt) acc[ra][nt] = MFMA16(af[s][ra], bf[s][nt], acc[ra][nt]);
.LBB0_1165:
	s_and_b32 s21, s26, 0xffffffe0
	s_addk_i32 s21, 0x2000
	s_and_b32 s20, s26, 31
	v_or_b32_e32 v8, s21, v30
	v_ashrrev_i32_e32 v9, 31, v8
	s_lshl_b32 s27, s20, 6
	v_lshlrev_b64 v[8:9], 12, v[8:9]
	v_or_b32_e32 v0, s27, v30
	v_lshl_add_u64 v[10:11], v[2:3], 0, v[8:9]
	v_lshlrev_b32_e32 v0, 12, v0
	v_lshl_add_u64 v[16:17], v[4:5], 0, v[0:1]
	v_add_co_u32_e32 v8, vcc, 0x10000, v10
	s_mov_b64 s[8:9], vcc
	v_add_co_u32_e32 v12, vcc, 0x10000, v16
	v_readfirstlane_b32 s36, v139
	s_lshr_b32 s36, s36, 6
	s_and_b32 s37, s26, 0xffffffe0
	s_addk_i32 s37, 0x2000
	s_and_b32 s38, s26, 31
	s_lshl_b32 s38, s38, 6
	s_lshl_b32 s39, s37, 12
	s_mul_i32 s40, s36, 0x200
	s_add_u32 s42, s18, s39
	s_addc_u32 s43, s19, 0
	s_add_u32 s42, s42, s40
	s_addc_u32 s43, s43, 0
	s_lshl_b32 s41, s24, 1
	s_lshl_b32 s39, s38, 12
	s_add_u32 s44, s22, s41
	s_addc_u32 s45, s23, 0
	s_add_u32 s44, s44, s39
	s_addc_u32 s45, s45, 0
	s_add_u32 s44, s44, s40
	s_addc_u32 s45, s45, 0
	v_lshrrev_b32_e32 v227, 3, v215
	v_and_b32_e32 v228, 7, v215
	v_lshlrev_b32_e32 v198, 12, v227
	v_lshl_add_u32 v198, v228, 4, v198
	v_add_u32_e32 v199, 0x8000, v198
	v_add_u32_e32 v200, 0x10000, v198
	v_add_u32_e32 v201, 0x18000, v198
	v_add_u32_e32 v202, 0x20000, v198
	v_add_u32_e32 v203, 0x28000, v198
	v_add_u32_e32 v204, 0x30000, v198
	v_add_u32_e32 v205, 0x38000, v198
	s_lshl_b32 s46, s36, 13
	s_mul_i32 s47, s36, 0x1800
	s_add_i32 s47, s47, 0x10000
	v_mul_u32_u24_e32 v206, 0x90, v227
	v_lshl_add_u32 v206, v228, 4, v206
	v_add_u32_e32 v207, s47, v206
	v_add_u32_e32 v206, s46, v206
	v_and_b32_e32 v227, 15, v215
	v_lshrrev_b32_e32 v228, 4, v215
	v_mul_u32_u24_e32 v208, 0x90, v227
	v_lshl_add_u32 v208, v228, 4, v208
	v_add_u32_e32 v209, s47, v208
	v_add_u32_e32 v208, s46, v208
	v_add_u32_e32 v226, 0x1b00, v208
	v_subrev_u32_e32 v228, 0x480, v209
	v_cmp_gt_u32_e32 vcc, 8, v227
	v_cndmask_b32_e32 v226, v228, v226, vcc
	global_load_dwordx4 v[34:37], v198, s[42:43]
	global_load_dwordx4 v[38:41], v199, s[42:43]
	global_load_dwordx4 v[42:45], v200, s[42:43]
	global_load_dwordx4 v[46:49], v201, s[42:43]
	global_load_dwordx4 v[50:53], v198, s[44:45]
	global_load_dwordx4 v[54:57], v199, s[44:45]
	global_load_dwordx4 v[58:61], v200, s[44:45]
	global_load_dwordx4 v[62:65], v201, s[44:45]
	global_load_dwordx4 v[66:69], v202, s[44:45]
	global_load_dwordx4 v[70:73], v203, s[44:45]
	global_load_dwordx4 v[74:77], v204, s[44:45]
	global_load_dwordx4 v[78:81], v205, s[44:45]
	global_load_dwordx4 v[82:85], v198, s[42:43] offset:128
	global_load_dwordx4 v[86:89], v199, s[42:43] offset:128
	global_load_dwordx4 v[90:93], v200, s[42:43] offset:128
	global_load_dwordx4 v[94:97], v201, s[42:43] offset:128
	global_load_dwordx4 v[98:101], v198, s[44:45] offset:128
	global_load_dwordx4 v[102:105], v199, s[44:45] offset:128
	global_load_dwordx4 v[106:109], v200, s[44:45] offset:128
	global_load_dwordx4 v[110:113], v201, s[44:45] offset:128
	global_load_dwordx4 v[114:117], v202, s[44:45] offset:128
	global_load_dwordx4 v[118:121], v203, s[44:45] offset:128
	global_load_dwordx4 v[122:125], v204, s[44:45] offset:128
	global_load_dwordx4 v[126:129], v205, s[44:45] offset:128
	s_waitcnt vmcnt(12)
	ds_write_b128 v206, v[34:37]
	ds_write_b128 v206, v[38:41] offset:1152
	ds_write_b128 v206, v[42:45] offset:2304
	ds_write_b128 v206, v[46:49] offset:3456
	ds_write_b128 v206, v[50:53] offset:4608
	ds_write_b128 v206, v[54:57] offset:5760
	ds_write_b128 v206, v[58:61] offset:6912
	ds_write_b128 v207, v[62:65]
	ds_write_b128 v207, v[66:69] offset:1152
	ds_write_b128 v207, v[70:73] offset:2304
	ds_write_b128 v207, v[74:77] offset:3456
	ds_write_b128 v207, v[78:81] offset:4608
	global_load_dwordx4 v[34:37], v198, s[42:43] offset:256
	global_load_dwordx4 v[38:41], v199, s[42:43] offset:256
	global_load_dwordx4 v[42:45], v200, s[42:43] offset:256
	global_load_dwordx4 v[46:49], v201, s[42:43] offset:256
	global_load_dwordx4 v[50:53], v198, s[44:45] offset:256
	global_load_dwordx4 v[54:57], v199, s[44:45] offset:256
	global_load_dwordx4 v[58:61], v200, s[44:45] offset:256
	global_load_dwordx4 v[62:65], v201, s[44:45] offset:256
	global_load_dwordx4 v[66:69], v202, s[44:45] offset:256
	global_load_dwordx4 v[70:73], v203, s[44:45] offset:256
	global_load_dwordx4 v[74:77], v204, s[44:45] offset:256
	global_load_dwordx4 v[78:81], v205, s[44:45] offset:256
	ds_read_b128 v[146:149], v208 offset:0
	ds_read_b128 v[150:153], v208 offset:2304
	ds_read_b128 v[154:157], v208 offset:4608
	ds_read_b128 v[158:161], v226
	ds_read_b128 v[162:165], v209 offset:1152
	ds_read_b128 v[166:169], v209 offset:3456
	ds_read_b128 v[170:173], v208 offset:64
	ds_read_b128 v[174:177], v208 offset:2368
	ds_read_b128 v[178:181], v208 offset:4672
	ds_read_b128 v[182:185], v226 offset:64
	ds_read_b128 v[186:189], v209 offset:1216
	ds_read_b128 v[190:193], v209 offset:3520
	s_waitcnt lgkmcnt(6)
	v_mfma_f32_16x16x32_bf16 v[8:11], v[146:149], v[154:157], 0
	v_mfma_f32_16x16x32_bf16 v[12:15], v[146:149], v[158:161], 0
	v_mfma_f32_16x16x32_bf16 v[16:19], v[146:149], v[162:165], 0
	v_mfma_f32_16x16x32_bf16 v[20:23], v[146:149], v[166:169], 0
	v_mfma_f32_16x16x32_bf16 v[24:27], v[150:153], v[154:157], 0
	v_mfma_f32_16x16x32_bf16 v[130:133], v[150:153], v[158:161], 0
	v_mfma_f32_16x16x32_bf16 v[134:137], v[150:153], v[162:165], 0
	v_mfma_f32_16x16x32_bf16 v[194:197], v[150:153], v[166:169], 0
	s_waitcnt lgkmcnt(0)
; #define MFMA16(a, b, c) __builtin_amdgcn_mfma_f32_16x16x32_bf16((a), (b), (c), 0, 0, 0)
; __device__ __forceinline__ void sample_out_block(LAS unsigned char* lds, const bf16_t* A, const bf16_t* Bt, int K, bf16_t* xb, float* sspart, int blk, int tid) {
;     ...
;         for (int k0 = 0; k0 < kq; k0 += 64) {
;             const int k1 = (k0 + 64 < kq) ? k0 + 64 : k0;
; #pragma unroll
;             for (int s = 0; s < 2; ++s) {
; #pragma unroll
;                 for (int ra = 0; ra < 2; ++ra) afn[s][ra] = *(const bf16x8*)(ap + (size_t)(16 * ra) * K + k1 + 32 * s);
; #pragma unroll
;                 for (int nt = 0; nt < 4; ++nt) bfn[s][nt] = *(const bf16x8*)(bp + (size_t)(16 * nt) * K + k1 + 32 * s);
;             }
; #pragma unroll
;             for (int s = 0; s < 2; ++s)
; #pragma unroll
;                 for (int ra = 0; ra < 2; ++ra)
; #pragma unroll
;                     for (int nt = 0; nt < 4; ++nt) acc[ra][nt] = MFMA16(af[s][ra], bf[s][nt], acc[ra][nt]);
; #pragma unroll
;             for (int s = 0; s < 2; ++s) {
; #pragma unroll
;                 for (int ra = 0; ra < 2; ++ra) af[s][ra] = afn[s][ra];
; #pragma unroll
;                 for (int nt = 0; nt < 4; ++nt) bf[s][nt] = bfn[s][nt];
;             }
;         }
	v_mfma_f32_16x16x32_bf16 v[8:11], v[170:173], v[178:181], v[8:11]
	v_mfma_f32_16x16x32_bf16 v[12:15], v[170:173], v[182:185], v[12:15]
	v_mfma_f32_16x16x32_bf16 v[16:19], v[170:173], v[186:189], v[16:19]
	v_mfma_f32_16x16x32_bf16 v[20:23], v[170:173], v[190:193], v[20:23]
	v_mfma_f32_16x16x32_bf16 v[24:27], v[174:177], v[178:181], v[24:27]
	v_mfma_f32_16x16x32_bf16 v[130:133], v[174:177], v[182:185], v[130:133]
	v_mfma_f32_16x16x32_bf16 v[134:137], v[174:177], v[186:189], v[134:137]
	v_mfma_f32_16x16x32_bf16 v[194:197], v[174:177], v[190:193], v[194:197]
	s_waitcnt vmcnt(12)
	ds_write_b128 v206, v[82:85]
	ds_write_b128 v206, v[86:89] offset:1152
	ds_write_b128 v206, v[90:93] offset:2304
	ds_write_b128 v206, v[94:97] offset:3456
	ds_write_b128 v206, v[98:101] offset:4608
	ds_write_b128 v206, v[102:105] offset:5760
	ds_write_b128 v206, v[106:109] offset:6912
	ds_write_b128 v207, v[110:113]
	ds_write_b128 v207, v[114:117] offset:1152
	ds_write_b128 v207, v[118:121] offset:2304
	ds_write_b128 v207, v[122:125] offset:3456
	ds_write_b128 v207, v[126:129] offset:4608
	global_load_dwordx4 v[82:85], v198, s[42:43] offset:384
	global_load_dwordx4 v[86:89], v199, s[42:43] offset:384
	global_load_dwordx4 v[90:93], v200, s[42:43] offset:384
	global_load_dwordx4 v[94:97], v201, s[42:43] offset:384
	global_load_dwordx4 v[98:101], v198, s[44:45] offset:384
	global_load_dwordx4 v[102:105], v199, s[44:45] offset:384
	global_load_dwordx4 v[106:109], v200, s[44:45] offset:384
	global_load_dwordx4 v[110:113], v201, s[44:45] offset:384
	global_load_dwordx4 v[114:117], v202, s[44:45] offset:384
	global_load_dwordx4 v[118:121], v203, s[44:45] offset:384
	global_load_dwordx4 v[122:125], v204, s[44:45] offset:384
	global_load_dwordx4 v[126:129], v205, s[44:45] offset:384
	ds_read_b128 v[146:149], v208 offset:0
	ds_read_b128 v[150:153], v208 offset:2304
	ds_read_b128 v[154:157], v208 offset:4608
	ds_read_b128 v[158:161], v226
	ds_read_b128 v[162:165], v209 offset:1152
	ds_read_b128 v[166:169], v209 offset:3456
	ds_read_b128 v[170:173], v208 offset:64
	ds_read_b128 v[174:177], v208 offset:2368
	ds_read_b128 v[178:181], v208 offset:4672
	ds_read_b128 v[182:185], v226 offset:64
	ds_read_b128 v[186:189], v209 offset:1216
	ds_read_b128 v[190:193], v209 offset:3520
	s_waitcnt lgkmcnt(6)
	v_mfma_f32_16x16x32_bf16 v[8:11], v[146:149], v[154:157], v[8:11]
	v_mfma_f32_16x16x32_bf16 v[12:15], v[146:149], v[158:161], v[12:15]
	v_mfma_f32_16x16x32_bf16 v[16:19], v[146:149], v[162:165], v[16:19]
	v_mfma_f32_16x16x32_bf16 v[20:23], v[146:149], v[166:169], v[20:23]
	v_mfma_f32_16x16x32_bf16 v[24:27], v[150:153], v[154:157], v[24:27]
	v_mfma_f32_16x16x32_bf16 v[130:133], v[150:153], v[158:161], v[130:133]
	v_mfma_f32_16x16x32_bf16 v[134:137], v[150:153], v[162:165], v[134:137]
	v_mfma_f32_16x16x32_bf16 v[194:197], v[150:153], v[166:169], v[194:197]
	s_waitcnt lgkmcnt(0)
	v_mfma_f32_16x16x32_bf16 v[8:11], v[170:173], v[178:181], v[8:11]
	v_mfma_f32_16x16x32_bf16 v[12:15], v[170:173], v[182:185], v[12:15]
	v_mfma_f32_16x16x32_bf16 v[16:19], v[170:173], v[186:189], v[16:19]
	v_mfma_f32_16x16x32_bf16 v[20:23], v[170:173], v[190:193], v[20:23]
	v_mfma_f32_16x16x32_bf16 v[24:27], v[174:177], v[178:181], v[24:27]
	v_mfma_f32_16x16x32_bf16 v[130:133], v[174:177], v[182:185], v[130:133]
	v_mfma_f32_16x16x32_bf16 v[134:137], v[174:177], v[186:189], v[134:137]
	v_mfma_f32_16x16x32_bf16 v[194:197], v[174:177], v[190:193], v[194:197]
	s_waitcnt vmcnt(12)
	ds_write_b128 v206, v[34:37]
	ds_write_b128 v206, v[38:41] offset:1152
	ds_write_b128 v206, v[42:45] offset:2304
	ds_write_b128 v206, v[46:49] offset:3456
	ds_write_b128 v206, v[50:53] offset:4608
	ds_write_b128 v206, v[54:57] offset:5760
	ds_write_b128 v206, v[58:61] offset:6912
	ds_write_b128 v207, v[62:65]
	ds_write_b128 v207, v[66:69] offset:1152
	ds_write_b128 v207, v[70:73] offset:2304
	ds_write_b128 v207, v[74:77] offset:3456
	ds_write_b128 v207, v[78:81] offset:4608
	ds_read_b128 v[146:149], v208 offset:0
	ds_read_b128 v[150:153], v208 offset:2304
	ds_read_b128 v[154:157], v208 offset:4608
	ds_read_b128 v[158:161], v226
	ds_read_b128 v[162:165], v209 offset:1152
	ds_read_b128 v[166:169], v209 offset:3456
	ds_read_b128 v[170:173], v208 offset:64
	ds_read_b128 v[174:177], v208 offset:2368
	ds_read_b128 v[178:181], v208 offset:4672
	ds_read_b128 v[182:185], v226 offset:64
	ds_read_b128 v[186:189], v209 offset:1216
	ds_read_b128 v[190:193], v209 offset:3520
	s_waitcnt lgkmcnt(6)
	v_mfma_f32_16x16x32_bf16 v[8:11], v[146:149], v[154:157], v[8:11]
	v_mfma_f32_16x16x32_bf16 v[12:15], v[146:149], v[158:161], v[12:15]
	v_mfma_f32_16x16x32_bf16 v[16:19], v[146:149], v[162:165], v[16:19]
	v_mfma_f32_16x16x32_bf16 v[20:23], v[146:149], v[166:169], v[20:23]
	v_mfma_f32_16x16x32_bf16 v[24:27], v[150:153], v[154:157], v[24:27]
	v_mfma_f32_16x16x32_bf16 v[130:133], v[150:153], v[158:161], v[130:133]
	v_mfma_f32_16x16x32_bf16 v[134:137], v[150:153], v[162:165], v[134:137]
	v_mfma_f32_16x16x32_bf16 v[194:197], v[150:153], v[166:169], v[194:197]
	s_waitcnt lgkmcnt(0)
	v_mfma_f32_16x16x32_bf16 v[8:11], v[170:173], v[178:181], v[8:11]
	v_mfma_f32_16x16x32_bf16 v[12:15], v[170:173], v[182:185], v[12:15]
	v_mfma_f32_16x16x32_bf16 v[16:19], v[170:173], v[186:189], v[16:19]
	v_mfma_f32_16x16x32_bf16 v[20:23], v[170:173], v[190:193], v[20:23]
	v_mfma_f32_16x16x32_bf16 v[24:27], v[174:177], v[178:181], v[24:27]
	v_mfma_f32_16x16x32_bf16 v[130:133], v[174:177], v[182:185], v[130:133]
	v_mfma_f32_16x16x32_bf16 v[134:137], v[174:177], v[186:189], v[134:137]
	v_mfma_f32_16x16x32_bf16 v[194:197], v[174:177], v[190:193], v[194:197]
	s_waitcnt vmcnt(0)
; #define LAS __attribute__((address_space(3)))
; #define MFMA16(a, b, c) __builtin_amdgcn_mfma_f32_16x16x32_bf16((a), (b), (c), 0, 0, 0)
; __device__ __forceinline__ float bf1(bf16_t h) { return __uint_as_float((unsigned)h << 16); }
; __device__ __forceinline__ bf16_t f2bf(float f) { return (bf16_t)(pk2(f, 0.f) & 0xffffu); }
; __device__ __forceinline__ void sample_out_block(LAS unsigned char* lds, const bf16_t* A, const bf16_t* Bt, int K, bf16_t* xb, float* sspart, int blk, int tid) {
;     ...
; #pragma unroll
;             for (int s = 0; s < 2; ++s)
; #pragma unroll
;                 for (int ra = 0; ra < 2; ++ra)
; #pragma unroll
;                     for (int nt = 0; nt < 4; ++nt) acc[ra][nt] = MFMA16(af[s][ra], bf[s][nt], acc[ra][nt]);
; #pragma unroll
;             for (int s = 0; s < 2; ++s) {
; #pragma unroll
;                 for (int ra = 0; ra < 2; ++ra) af[s][ra] = afn[s][ra];
; #pragma unroll
;                 for (int nt = 0; nt < 4; ++nt) bf[s][nt] = bfn[s][nt];
;             }
;         }
;     }
;     LAS f32x4* part = (LAS f32x4*)lds;
; #pragma unroll
;     for (int ra = 0; ra < 2; ++ra)
; #pragma unroll
;         for (int nt = 0; nt < 4; ++nt) part[(wave * 8 + ra * 4 + nt) * 64 + lane] = acc[ra][nt];
;     __syncthreads();
;     if (wave < 2) {
;         const int ra = wave;
;         f32x4 sum[4];
; #pragma unroll
;         for (int nt = 0; nt < 4; ++nt) {
;             sum[nt] = part[(0 * 8 + ra * 4 + nt) * 64 + lane];
; #pragma unroll
;             for (int w = 1; w < 8; ++w) sum[nt] += part[(w * 8 + ra * 4 + nt) * 64 + lane];
;         }
;         float ss[4] = {0.f, 0.f, 0.f, 0.f};
; #pragma unroll
;         for (int j = 0; j < 4; ++j)
; #pragma unroll
;             for (int nt = 0; nt < 4; ++nt) {
;                 bf16_t* xp = xb + (size_t)(r0 + 16 * ra + 4 * g + j) * 2048 + 64 * cg + 16 * nt + l15;
;                 const bf16_t nv = f2bf(bf1(*xp) + sum[nt][j]);
;                 *xp = nv; const float r = bf1(nv); ss[j] += r * r;
	ds_write_b128 v206, v[82:85]
	ds_write_b128 v206, v[86:89] offset:1152
	ds_write_b128 v206, v[90:93] offset:2304
	ds_write_b128 v206, v[94:97] offset:3456
	ds_write_b128 v206, v[98:101] offset:4608
	ds_write_b128 v206, v[102:105] offset:5760
	ds_write_b128 v206, v[106:109] offset:6912
	ds_write_b128 v207, v[110:113]
	ds_write_b128 v207, v[114:117] offset:1152
	ds_write_b128 v207, v[118:121] offset:2304
	ds_write_b128 v207, v[122:125] offset:3456
	ds_write_b128 v207, v[126:129] offset:4608
	ds_read_b128 v[146:149], v208 offset:0
	ds_read_b128 v[150:153], v208 offset:2304
	ds_read_b128 v[154:157], v208 offset:4608
	ds_read_b128 v[158:161], v226
	ds_read_b128 v[162:165], v209 offset:1152
	ds_read_b128 v[166:169], v209 offset:3456
	ds_read_b128 v[170:173], v208 offset:64
	ds_read_b128 v[174:177], v208 offset:2368
	ds_read_b128 v[178:181], v208 offset:4672
	ds_read_b128 v[182:185], v226 offset:64
	ds_read_b128 v[186:189], v209 offset:1216
	ds_read_b128 v[190:193], v209 offset:3520
	s_waitcnt lgkmcnt(6)
	v_mfma_f32_16x16x32_bf16 v[8:11], v[146:149], v[154:157], v[8:11]
	v_mfma_f32_16x16x32_bf16 v[12:15], v[146:149], v[158:161], v[12:15]
	v_mfma_f32_16x16x32_bf16 v[16:19], v[146:149], v[162:165], v[16:19]
	v_mfma_f32_16x16x32_bf16 v[20:23], v[146:149], v[166:169], v[20:23]
	v_mfma_f32_16x16x32_bf16 v[24:27], v[150:153], v[154:157], v[24:27]
	v_mfma_f32_16x16x32_bf16 v[130:133], v[150:153], v[158:161], v[130:133]
	v_mfma_f32_16x16x32_bf16 v[134:137], v[150:153], v[162:165], v[134:137]
	v_mfma_f32_16x16x32_bf16 v[194:197], v[150:153], v[166:169], v[194:197]
	s_waitcnt lgkmcnt(0)
	v_mfma_f32_16x16x32_bf16 v[8:11], v[170:173], v[178:181], v[8:11]
	v_mfma_f32_16x16x32_bf16 v[12:15], v[170:173], v[182:185], v[12:15]
	v_mfma_f32_16x16x32_bf16 v[16:19], v[170:173], v[186:189], v[16:19]
	v_mfma_f32_16x16x32_bf16 v[20:23], v[170:173], v[190:193], v[20:23]
	v_mfma_f32_16x16x32_bf16 v[24:27], v[174:177], v[178:181], v[24:27]
	v_mfma_f32_16x16x32_bf16 v[130:133], v[174:177], v[182:185], v[130:133]
	v_mfma_f32_16x16x32_bf16 v[134:137], v[174:177], v[186:189], v[134:137]
	v_mfma_f32_16x16x32_bf16 v[194:197], v[174:177], v[190:193], v[194:197]
	s_nop 7
	s_nop 7
	ds_write_b128 v32, v[8:11]
	ds_write_b128 v32, v[12:15] offset:1024
	ds_write_b128 v32, v[16:19] offset:2048
	ds_write_b128 v32, v[20:23] offset:3072
	ds_write_b128 v32, v[24:27] offset:4096
	ds_write_b128 v32, v[130:133] offset:5120
	ds_write_b128 v32, v[134:137] offset:6144
	ds_write_b128 v32, v[194:197] offset:7168
	s_waitcnt lgkmcnt(0)
	s_barrier
	s_and_saveexec_b64 s[8:9], s[4:5]
	s_cbranch_execz .LBB0_1164
	v_add_u32_e32 v170, s21, v31
	v_lshlrev_b32_e32 v170, 12, v170
	s_lshl_b32 s36, s27, 1
	v_add_u32_e32 v170, s36, v170
	v_mov_b32_e32 v171, 0
	s_mov_b64 s[38:39], 0x1000
	v_lshl_add_u64 v[162:163], v[6:7], 0, v[170:171]
	v_lshl_add_u64 v[164:165], v[162:163], 0, s[38:39]
	v_lshl_add_u64 v[166:167], v[164:165], 0, s[38:39]
	v_lshl_add_u64 v[168:169], v[166:167], 0, s[38:39]
	global_load_ushort v146, v[162:163], off
	global_load_ushort v147, v[162:163], off offset:32
	global_load_ushort v148, v[162:163], off offset:64
	global_load_ushort v149, v[162:163], off offset:96
	global_load_ushort v150, v[164:165], off
	global_load_ushort v151, v[164:165], off offset:32
	global_load_ushort v152, v[164:165], off offset:64
	global_load_ushort v153, v[164:165], off offset:96
	global_load_ushort v154, v[166:167], off
	global_load_ushort v155, v[166:167], off offset:32
	global_load_ushort v156, v[166:167], off offset:64
	global_load_ushort v157, v[166:167], off offset:96
	global_load_ushort v158, v[168:169], off
	global_load_ushort v159, v[168:169], off offset:32
	global_load_ushort v160, v[168:169], off offset:64
	global_load_ushort v161, v[168:169], off offset:96
	ds_read_b128 v[8:11], v33
	ds_read_b128 v[12:15], v33 offset:8192
	s_lshl_b32 s80, s27, 1
	v_lshl_add_u64 v[28:29], v[6:7], 0, s[80:81]
	s_lshl_b32 s10, s20, 2
	s_add_u32 s10, s16, s10
	s_waitcnt lgkmcnt(0)
	v_pk_add_f32 v[14:15], v[10:11], v[14:15]
	v_pk_add_f32 v[12:13], v[8:9], v[12:13]
	ds_read_b128 v[8:11], v33 offset:16384
	s_addc_u32 s11, s17, 0
	s_waitcnt lgkmcnt(0)
	v_pk_add_f32 v[14:15], v[14:15], v[10:11]
	v_pk_add_f32 v[12:13], v[12:13], v[8:9]
	ds_read_b128 v[8:11], v33 offset:24576
	s_waitcnt lgkmcnt(0)
	v_pk_add_f32 v[14:15], v[14:15], v[10:11]
	v_pk_add_f32 v[12:13], v[12:13], v[8:9]
	ds_read_b128 v[8:11], v33 offset:32768
	s_waitcnt lgkmcnt(0)
	v_pk_add_f32 v[14:15], v[14:15], v[10:11]
	v_pk_add_f32 v[12:13], v[12:13], v[8:9]
	ds_read_b128 v[8:11], v33 offset:40960
	s_waitcnt lgkmcnt(0)
	v_pk_add_f32 v[14:15], v[14:15], v[10:11]
	v_pk_add_f32 v[12:13], v[12:13], v[8:9]
	ds_read_b128 v[8:11], v33 offset:49152
	s_waitcnt lgkmcnt(0)
	v_pk_add_f32 v[14:15], v[14:15], v[10:11]
	v_pk_add_f32 v[16:17], v[12:13], v[8:9]
	ds_read_b128 v[8:11], v33 offset:57344
	s_waitcnt lgkmcnt(0)
	v_pk_add_f32 v[12:13], v[14:15], v[10:11]
	v_pk_add_f32 v[20:21], v[16:17], v[8:9]
	ds_read_b128 v[8:11], v33 offset:1024
	ds_read_b128 v[14:17], v33 offset:9216
	s_waitcnt lgkmcnt(0)
	v_pk_add_f32 v[16:17], v[10:11], v[16:17]
	v_pk_add_f32 v[14:15], v[8:9], v[14:15]
	ds_read_b128 v[8:11], v33 offset:17408
	s_waitcnt lgkmcnt(0)
	v_pk_add_f32 v[16:17], v[16:17], v[10:11]
	v_pk_add_f32 v[14:15], v[14:15], v[8:9]
	ds_read_b128 v[8:11], v33 offset:25600
	s_waitcnt lgkmcnt(0)
	v_pk_add_f32 v[16:17], v[16:17], v[10:11]
	v_pk_add_f32 v[14:15], v[14:15], v[8:9]
	ds_read_b128 v[8:11], v33 offset:33792
	s_waitcnt lgkmcnt(0)
	v_pk_add_f32 v[16:17], v[16:17], v[10:11]
	v_pk_add_f32 v[14:15], v[14:15], v[8:9]
	ds_read_b128 v[8:11], v33 offset:41984
	s_waitcnt lgkmcnt(0)
; __device__ __forceinline__ float bf1(bf16_t h) { return __uint_as_float((unsigned)h << 16); }
; __device__ __forceinline__ bf16_t f2bf(float f) { return (bf16_t)(pk2(f, 0.f) & 0xffffu); }
; __device__ __forceinline__ void sample_out_block(LAS unsigned char* lds, const bf16_t* A, const bf16_t* Bt, int K, bf16_t* xb, float* sspart, int blk, int tid) {
;     ...
;         const int ra = wave;
;         f32x4 sum[4];
; #pragma unroll
;         for (int nt = 0; nt < 4; ++nt) {
;             sum[nt] = part[(0 * 8 + ra * 4 + nt) * 64 + lane];
; #pragma unroll
;             for (int w = 1; w < 8; ++w) sum[nt] += part[(w * 8 + ra * 4 + nt) * 64 + lane];
;         }
;         float ss[4] = {0.f, 0.f, 0.f, 0.f};
; #pragma unroll
;         for (int j = 0; j < 4; ++j)
; #pragma unroll
;             for (int nt = 0; nt < 4; ++nt) {
;                 bf16_t* xp = xb + (size_t)(r0 + 16 * ra + 4 * g + j) * 2048 + 64 * cg + 16 * nt + l15;
;                 const bf16_t nv = f2bf(bf1(*xp) + sum[nt][j]);
;                 *xp = nv; const float r = bf1(nv); ss[j] += r * r;
;             }
; #pragma unroll
;         for (int j = 0; j < 4; ++j) {
;             float s = ss[j];
;             s += __shfl_xor(s, 1); s += __shfl_xor(s, 2); s += __shfl_xor(s, 4); s += __shfl_xor(s, 8);
;             if (l15 == 0) sspart[(size_t)(r0 + 16 * ra + 4 * g + j) * 32 + cg] = s;
	v_pk_add_f32 v[16:17], v[16:17], v[10:11]
	v_pk_add_f32 v[14:15], v[14:15], v[8:9]
	ds_read_b128 v[8:11], v33 offset:50176
	s_waitcnt lgkmcnt(0)
	v_pk_add_f32 v[16:17], v[16:17], v[10:11]
	v_pk_add_f32 v[14:15], v[14:15], v[8:9]
	ds_read_b128 v[8:11], v33 offset:58368
	s_waitcnt lgkmcnt(0)
	v_pk_add_f32 v[18:19], v[16:17], v[10:11]
	v_pk_add_f32 v[26:27], v[14:15], v[8:9]
	ds_read_b128 v[8:11], v33 offset:2048
	ds_read_b128 v[14:17], v33 offset:10240
	s_waitcnt lgkmcnt(0)
	v_pk_add_f32 v[16:17], v[10:11], v[16:17]
	v_pk_add_f32 v[14:15], v[8:9], v[14:15]
	ds_read_b128 v[8:11], v33 offset:18432
	s_waitcnt lgkmcnt(0)
	v_pk_add_f32 v[16:17], v[16:17], v[10:11]
	v_pk_add_f32 v[14:15], v[14:15], v[8:9]
	ds_read_b128 v[8:11], v33 offset:26624
	s_waitcnt lgkmcnt(0)
	v_pk_add_f32 v[16:17], v[16:17], v[10:11]
	v_pk_add_f32 v[14:15], v[14:15], v[8:9]
	ds_read_b128 v[8:11], v33 offset:34816
	s_waitcnt lgkmcnt(0)
	v_pk_add_f32 v[16:17], v[16:17], v[10:11]
	v_pk_add_f32 v[14:15], v[14:15], v[8:9]
	ds_read_b128 v[8:11], v33 offset:43008
	s_waitcnt lgkmcnt(0)
	v_pk_add_f32 v[16:17], v[16:17], v[10:11]
	v_pk_add_f32 v[14:15], v[14:15], v[8:9]
	ds_read_b128 v[8:11], v33 offset:51200
	s_waitcnt lgkmcnt(0)
	v_pk_add_f32 v[16:17], v[16:17], v[10:11]
	v_pk_add_f32 v[14:15], v[14:15], v[8:9]
	ds_read_b128 v[8:11], v33 offset:59392
	s_waitcnt lgkmcnt(0)
	v_pk_add_f32 v[16:17], v[16:17], v[10:11]
	v_pk_add_f32 v[24:25], v[14:15], v[8:9]
	ds_read_b128 v[8:11], v33 offset:3072
	ds_read_b128 v[34:37], v33 offset:11264
	s_waitcnt lgkmcnt(0)
	v_pk_add_f32 v[14:15], v[10:11], v[36:37]
	v_pk_add_f32 v[22:23], v[8:9], v[34:35]
	ds_read_b128 v[8:11], v33 offset:19456
	ds_read_b128 v[34:37], v33 offset:60416
	s_waitcnt lgkmcnt(1)
	v_pk_add_f32 v[14:15], v[14:15], v[10:11]
	v_pk_add_f32 v[22:23], v[22:23], v[8:9]
	ds_read_b128 v[8:11], v33 offset:27648
	s_waitcnt lgkmcnt(0)
	v_pk_add_f32 v[14:15], v[14:15], v[10:11]
	v_pk_add_f32 v[22:23], v[22:23], v[8:9]
	ds_read_b128 v[8:11], v33 offset:35840
	s_waitcnt lgkmcnt(0)
	v_pk_add_f32 v[14:15], v[14:15], v[10:11]
	v_pk_add_f32 v[22:23], v[22:23], v[8:9]
	ds_read_b128 v[8:11], v33 offset:44032
	s_waitcnt lgkmcnt(0)
	v_pk_add_f32 v[14:15], v[14:15], v[10:11]
	v_pk_add_f32 v[22:23], v[22:23], v[8:9]
	ds_read_b128 v[8:11], v33 offset:52224
	s_waitcnt lgkmcnt(0)
	v_pk_add_f32 v[10:11], v[14:15], v[10:11]
	v_pk_add_f32 v[14:15], v[22:23], v[8:9]
	v_pk_add_f32 v[8:9], v[10:11], v[36:37]
	v_add_u32_e32 v10, s21, v31
	v_ashrrev_i32_e32 v11, 31, v10
	v_pk_add_f32 v[22:23], v[14:15], v[34:35]
	v_lshlrev_b64 v[14:15], 12, v[10:11]
	v_lshl_add_u64 v[14:15], v[28:29], 0, v[14:15]
	s_waitcnt vmcnt(0)
	v_mov_b32_e32 v0, v146
	v_lshlrev_b32_e32 v0, 16, v0
	v_add_f32_e32 v0, v20, v0
	v_cvt_pk_bf16_f32 v0, v0, s0
	global_store_short v[14:15], v0, off
	v_lshlrev_b32_e32 v20, 16, v0
	v_mov_b32_e32 v0, v147
	v_lshlrev_b32_e32 v0, 16, v0
	v_add_f32_e32 v0, v26, v0
	v_cvt_pk_bf16_f32 v0, v0, s0
	global_store_short v[14:15], v0, off offset:32
	v_lshlrev_b32_e32 v0, 16, v0
	v_mul_f32_e32 v0, v0, v0
	v_fmac_f32_e32 v0, v20, v20
	v_mov_b32_e32 v20, v148
	v_lshlrev_b32_e32 v20, 16, v20
	v_add_f32_e32 v20, v24, v20
	v_cvt_pk_bf16_f32 v20, v20, s0
	global_store_short v[14:15], v20, off offset:64
	v_lshlrev_b32_e32 v20, 16, v20
	v_fmac_f32_e32 v0, v20, v20
	v_mov_b32_e32 v20, v149
	v_lshlrev_b32_e32 v20, 16, v20
	v_add_f32_e32 v20, v22, v20
	v_cvt_pk_bf16_f32 v20, v20, s0
	global_store_short v[14:15], v20, off offset:96
	v_lshlrev_b32_e32 v14, 16, v20
	v_fmac_f32_e32 v0, v14, v14
	v_or_b32_e32 v14, 1, v10
	v_ashrrev_i32_e32 v15, 31, v14
	v_lshlrev_b64 v[34:35], 12, v[14:15]
	v_lshl_add_u64 v[36:37], v[28:29], 0, v[34:35]
	v_mov_b32_e32 v20, v150
	v_lshlrev_b32_e32 v20, 16, v20
	v_add_f32_e32 v20, v21, v20
	v_cvt_pk_bf16_f32 v26, v20, s0
	v_mov_b32_e32 v20, v151
	v_lshlrev_b32_e32 v20, 16, v20
	v_add_f32_e32 v20, v27, v20
	v_cvt_pk_bf16_f32 v27, v20, s0
	v_mov_b32_e32 v20, v152
	v_lshlrev_b32_e32 v20, 16, v20
	v_add_f32_e32 v20, v25, v20
	v_cvt_pk_bf16_f32 v34, v20, s0
	v_mov_b32_e32 v20, v153
	v_lshlrev_b32_e32 v20, 16, v20
	v_add_f32_e32 v20, v23, v20
	v_cvt_pk_bf16_f32 v35, v20, s0
	v_or_b32_e32 v20, 2, v10
	v_ashrrev_i32_e32 v21, 31, v20
	v_lshlrev_b64 v[22:23], 12, v[20:21]
	v_lshl_add_u64 v[22:23], v[28:29], 0, v[22:23]
	v_mov_b32_e32 v24, v154
	v_lshlrev_b32_e32 v24, 16, v24
	v_add_f32_e32 v12, v12, v24
	v_mov_b32_e32 v24, v155
	v_cvt_pk_bf16_f32 v12, v12, s0
	global_store_short v[22:23], v12, off
	global_store_short v[36:37], v26, off
	global_store_short v[36:37], v27, off offset:32
	global_store_short v[36:37], v34, off offset:64
	global_store_short v[36:37], v35, off offset:96
	v_xor_b32_e32 v36, 8, v215
	s_waitcnt vmcnt(5)
	v_lshlrev_b32_e32 v24, 16, v24
	v_add_f32_e32 v18, v18, v24
	v_mov_b32_e32 v24, v156
	v_cvt_pk_bf16_f32 v18, v18, s0
	global_store_short v[22:23], v18, off offset:32
	s_waitcnt vmcnt(1)
	v_lshlrev_b32_e32 v24, 16, v24
	v_add_f32_e32 v16, v16, v24
	v_mov_b32_e32 v24, v157
	v_cvt_pk_bf16_f32 v16, v16, s0
	global_store_short v[22:23], v16, off offset:64
	s_waitcnt vmcnt(1)
	v_lshlrev_b32_e32 v24, 16, v24
	v_add_f32_e32 v8, v8, v24
	v_cvt_pk_bf16_f32 v8, v8, s0
	global_store_short v[22:23], v8, off offset:96
	v_or_b32_e32 v22, 3, v10
	v_ashrrev_i32_e32 v23, 31, v22
	v_lshlrev_b64 v[24:25], 12, v[22:23]
	v_lshl_add_u64 v[24:25], v[28:29], 0, v[24:25]
	v_mov_b32_e32 v28, v158
	v_lshlrev_b32_e32 v28, 16, v28
	v_add_f32_e32 v13, v13, v28
	v_mov_b32_e32 v28, v159
	v_cvt_pk_bf16_f32 v13, v13, s0
	global_store_short v[24:25], v13, off
	s_waitcnt vmcnt(1)
	v_lshlrev_b32_e32 v28, 16, v28
	v_add_f32_e32 v19, v19, v28
	v_mov_b32_e32 v28, v160
	v_cvt_pk_bf16_f32 v19, v19, s0
	global_store_short v[24:25], v19, off offset:32
	s_waitcnt vmcnt(1)
	v_lshlrev_b32_e32 v28, 16, v28
	v_add_f32_e32 v17, v17, v28
	v_mov_b32_e32 v28, v161
	v_cvt_pk_bf16_f32 v17, v17, s0
	global_store_short v[24:25], v17, off offset:64
	s_waitcnt vmcnt(1)
	v_lshlrev_b32_e32 v28, 16, v28
	v_add_f32_e32 v9, v9, v28
	v_cvt_pk_bf16_f32 v9, v9, s0
	global_store_short v[24:25], v9, off offset:96
	v_and_b32_e32 v25, 64, v215
	v_xor_b32_e32 v24, 1, v215
	v_add_u32_e32 v29, 64, v25
	v_cmp_lt_i32_e32 vcc, v24, v29
	v_xor_b32_e32 v25, 2, v215
	v_xor_b32_e32 v28, 4, v215
	v_cndmask_b32_e32 v24, v215, v24, vcc
	v_cmp_lt_i32_e32 vcc, v25, v29
	v_lshlrev_b32_e32 v24, 2, v24
	s_nop 0
	v_cndmask_b32_e32 v25, v215, v25, vcc
	v_cmp_lt_i32_e32 vcc, v28, v29
	v_lshlrev_b32_e32 v25, 2, v25
	s_nop 0
	v_cndmask_b32_e32 v28, v215, v28, vcc
	v_cmp_lt_i32_e32 vcc, v36, v29
	v_lshlrev_b32_e32 v28, 2, v28
	s_nop 0
	v_cndmask_b32_e32 v29, v215, v36, vcc
	ds_bpermute_b32 v36, v24, v0
	v_lshlrev_b32_e32 v29, 2, v29
	s_waitcnt lgkmcnt(0)
	v_add_f32_e32 v0, v0, v36
	ds_bpermute_b32 v36, v25, v0
	s_waitcnt lgkmcnt(0)
	v_add_f32_e32 v0, v0, v36
	ds_bpermute_b32 v36, v28, v0
	s_waitcnt lgkmcnt(0)
	v_add_f32_e32 v0, v0, v36
	ds_bpermute_b32 v36, v29, v0
	s_and_saveexec_b64 s[20:21], s[6:7]
	s_cbranch_execz .LBB0_1168
; __device__ __forceinline__ void sample_out_block(LAS unsigned char* lds, const bf16_t* A, const bf16_t* Bt, int K, bf16_t* xb, float* sspart, int blk, int tid) {
;     ...
;         for (int j = 0; j < 4; ++j) {
;             float s = ss[j];
;             s += __shfl_xor(s, 1); s += __shfl_xor(s, 2); s += __shfl_xor(s, 4); s += __shfl_xor(s, 8);
;             if (l15 == 0) sspart[(size_t)(r0 + 16 * ra + 4 * g + j) * 32 + cg] = s;
;         }
	v_lshlrev_b64 v[10:11], 7, v[10:11]
	v_lshl_add_u64 v[10:11], s[10:11], 0, v[10:11]
	s_waitcnt lgkmcnt(0)
	v_add_f32_e32 v0, v0, v36
	global_store_dword v[10:11], v0, off
